# prep GEMVs: adaLN partial GEMV and shift@W bias GEMV keep 16 weight-row loads in flight (rolling window) instead of waiting per row / per 4 rows
# speedup vs baseline: 1.0144x; 1.0026x over previous
.LBB0_15:
	v_lshl_add_u64 v[140:141], v[26:27], 0, v[34:35]
	v_lshl_add_u64 v[142:143], v[26:27], 0, v[32:33]
	v_lshl_add_u64 v[144:145], v[26:27], 0, v[30:31]
	v_lshl_add_u64 v[146:147], v[26:27], 0, v[28:29]
	global_load_dwordx4 v[76:79], v[140:141], off
	global_load_dwordx4 v[80:83], v[142:143], off
	global_load_dwordx4 v[84:87], v[144:145], off
	global_load_dwordx4 v[88:91], v[146:147], off
	v_lshl_add_u64 v[26:27], v[26:27], 0, v[22:23]
	v_lshl_add_u64 v[140:141], v[26:27], 0, v[34:35]
	v_lshl_add_u64 v[142:143], v[26:27], 0, v[32:33]
	v_lshl_add_u64 v[144:145], v[26:27], 0, v[30:31]
	v_lshl_add_u64 v[146:147], v[26:27], 0, v[28:29]
	global_load_dwordx4 v[92:95], v[140:141], off
	global_load_dwordx4 v[96:99], v[142:143], off
	global_load_dwordx4 v[100:103], v[144:145], off
	global_load_dwordx4 v[104:107], v[146:147], off
	v_lshl_add_u64 v[26:27], v[26:27], 0, v[22:23]
	v_lshl_add_u64 v[140:141], v[26:27], 0, v[34:35]
	v_lshl_add_u64 v[142:143], v[26:27], 0, v[32:33]
	v_lshl_add_u64 v[144:145], v[26:27], 0, v[30:31]
	v_lshl_add_u64 v[146:147], v[26:27], 0, v[28:29]
	global_load_dwordx4 v[108:111], v[140:141], off
	global_load_dwordx4 v[112:115], v[142:143], off
	global_load_dwordx4 v[116:119], v[144:145], off
	global_load_dwordx4 v[120:123], v[146:147], off
	v_lshl_add_u64 v[26:27], v[26:27], 0, v[22:23]
	v_lshl_add_u64 v[140:141], v[26:27], 0, v[34:35]
	v_lshl_add_u64 v[142:143], v[26:27], 0, v[32:33]
	v_lshl_add_u64 v[144:145], v[26:27], 0, v[30:31]
	v_lshl_add_u64 v[146:147], v[26:27], 0, v[28:29]
	global_load_dwordx4 v[124:127], v[140:141], off
	global_load_dwordx4 v[128:131], v[142:143], off
	global_load_dwordx4 v[132:135], v[144:145], off
	global_load_dwordx4 v[136:139], v[146:147], off
	v_lshl_add_u64 v[26:27], v[26:27], 0, v[22:23]
	ds_read_b128 v[52:55], v25
	ds_read_b128 v[56:59], v25 offset:4096
	ds_read_b128 v[60:63], v25 offset:8192
	ds_read_b128 v[64:67], v25 offset:12288
	s_waitcnt lgkmcnt(0)
	v_mov_b32_e32 v68, v55
	v_mov_b32_e32 v70, v59
	v_mov_b32_e32 v72, v63
	v_mov_b32_e32 v74, v67
	s_waitcnt vmcnt(15)
	v_pk_fma_f32 v[14:15], v[76:77], v[52:53], v[14:15] op_sel_hi:[1,0,1]
	v_pk_fma_f32 v[16:17], v[78:79], v[52:53], v[16:17] op_sel_hi:[1,0,1]
	v_pk_fma_f32 v[10:11], v[76:77], v[56:57], v[10:11] op_sel_hi:[1,0,1]
	v_pk_fma_f32 v[12:13], v[78:79], v[56:57], v[12:13] op_sel_hi:[1,0,1]
	v_pk_fma_f32 v[6:7], v[76:77], v[60:61], v[6:7] op_sel_hi:[1,0,1]
	v_pk_fma_f32 v[8:9], v[78:79], v[60:61], v[8:9] op_sel_hi:[1,0,1]
	v_pk_fma_f32 v[2:3], v[76:77], v[64:65], v[2:3] op_sel_hi:[1,0,1]
	v_pk_fma_f32 v[4:5], v[78:79], v[64:65], v[4:5] op_sel_hi:[1,0,1]
	s_waitcnt vmcnt(14)
	v_pk_fma_f32 v[14:15], v[80:81], v[52:53], v[14:15] op_sel:[0,1,0]
	v_pk_fma_f32 v[16:17], v[82:83], v[52:53], v[16:17] op_sel:[0,1,0]
	v_pk_fma_f32 v[10:11], v[80:81], v[56:57], v[10:11] op_sel:[0,1,0]
	v_pk_fma_f32 v[12:13], v[82:83], v[56:57], v[12:13] op_sel:[0,1,0]
	v_pk_fma_f32 v[6:7], v[80:81], v[60:61], v[6:7] op_sel:[0,1,0]
	v_pk_fma_f32 v[8:9], v[82:83], v[60:61], v[8:9] op_sel:[0,1,0]
	v_pk_fma_f32 v[2:3], v[80:81], v[64:65], v[2:3] op_sel:[0,1,0]
	v_pk_fma_f32 v[4:5], v[82:83], v[64:65], v[4:5] op_sel:[0,1,0]
	s_waitcnt vmcnt(13)
	v_pk_fma_f32 v[14:15], v[84:85], v[54:55], v[14:15] op_sel_hi:[1,0,1]
	v_pk_fma_f32 v[16:17], v[86:87], v[54:55], v[16:17] op_sel_hi:[1,0,1]
	v_pk_fma_f32 v[10:11], v[84:85], v[58:59], v[10:11] op_sel_hi:[1,0,1]
	v_pk_fma_f32 v[12:13], v[86:87], v[58:59], v[12:13] op_sel_hi:[1,0,1]
	v_pk_fma_f32 v[6:7], v[84:85], v[62:63], v[6:7] op_sel_hi:[1,0,1]
	v_pk_fma_f32 v[8:9], v[86:87], v[62:63], v[8:9] op_sel_hi:[1,0,1]
	v_pk_fma_f32 v[2:3], v[84:85], v[66:67], v[2:3] op_sel_hi:[1,0,1]
	v_pk_fma_f32 v[4:5], v[86:87], v[66:67], v[4:5] op_sel_hi:[1,0,1]
	s_waitcnt vmcnt(12)
	v_pk_fma_f32 v[14:15], v[88:89], v[68:69], v[14:15] op_sel_hi:[1,0,1]
	v_pk_fma_f32 v[16:17], v[90:91], v[68:69], v[16:17] op_sel_hi:[1,0,1]
	v_pk_fma_f32 v[10:11], v[88:89], v[70:71], v[10:11] op_sel_hi:[1,0,1]
	v_pk_fma_f32 v[12:13], v[90:91], v[70:71], v[12:13] op_sel_hi:[1,0,1]
	v_pk_fma_f32 v[6:7], v[88:89], v[72:73], v[6:7] op_sel_hi:[1,0,1]
	v_pk_fma_f32 v[8:9], v[90:91], v[72:73], v[8:9] op_sel_hi:[1,0,1]
	v_pk_fma_f32 v[2:3], v[88:89], v[74:75], v[2:3] op_sel_hi:[1,0,1]
	v_pk_fma_f32 v[4:5], v[90:91], v[74:75], v[4:5] op_sel_hi:[1,0,1]
	v_lshl_add_u64 v[140:141], v[26:27], 0, v[34:35]
	v_lshl_add_u64 v[142:143], v[26:27], 0, v[32:33]
	v_lshl_add_u64 v[144:145], v[26:27], 0, v[30:31]
	v_lshl_add_u64 v[146:147], v[26:27], 0, v[28:29]
	global_load_dwordx4 v[76:79], v[140:141], off
	global_load_dwordx4 v[80:83], v[142:143], off
	global_load_dwordx4 v[84:87], v[144:145], off
	global_load_dwordx4 v[88:91], v[146:147], off
	v_lshl_add_u64 v[26:27], v[26:27], 0, v[22:23]
	ds_read_b128 v[52:55], v25 offset:16
	ds_read_b128 v[56:59], v25 offset:4112
	ds_read_b128 v[60:63], v25 offset:8208
	ds_read_b128 v[64:67], v25 offset:12304
	s_waitcnt lgkmcnt(0)
	v_mov_b32_e32 v68, v55
	v_mov_b32_e32 v70, v59
	v_mov_b32_e32 v72, v63
	v_mov_b32_e32 v74, v67
	s_waitcnt vmcnt(15)
	v_pk_fma_f32 v[14:15], v[92:93], v[52:53], v[14:15] op_sel_hi:[1,0,1]
	v_pk_fma_f32 v[16:17], v[94:95], v[52:53], v[16:17] op_sel_hi:[1,0,1]
	v_pk_fma_f32 v[10:11], v[92:93], v[56:57], v[10:11] op_sel_hi:[1,0,1]
	v_pk_fma_f32 v[12:13], v[94:95], v[56:57], v[12:13] op_sel_hi:[1,0,1]
	v_pk_fma_f32 v[6:7], v[92:93], v[60:61], v[6:7] op_sel_hi:[1,0,1]
	v_pk_fma_f32 v[8:9], v[94:95], v[60:61], v[8:9] op_sel_hi:[1,0,1]
	v_pk_fma_f32 v[2:3], v[92:93], v[64:65], v[2:3] op_sel_hi:[1,0,1]
	v_pk_fma_f32 v[4:5], v[94:95], v[64:65], v[4:5] op_sel_hi:[1,0,1]
	s_waitcnt vmcnt(14)
	v_pk_fma_f32 v[14:15], v[96:97], v[52:53], v[14:15] op_sel:[0,1,0]
	v_pk_fma_f32 v[16:17], v[98:99], v[52:53], v[16:17] op_sel:[0,1,0]
	v_pk_fma_f32 v[10:11], v[96:97], v[56:57], v[10:11] op_sel:[0,1,0]
	v_pk_fma_f32 v[12:13], v[98:99], v[56:57], v[12:13] op_sel:[0,1,0]
	v_pk_fma_f32 v[6:7], v[96:97], v[60:61], v[6:7] op_sel:[0,1,0]
	v_pk_fma_f32 v[8:9], v[98:99], v[60:61], v[8:9] op_sel:[0,1,0]
	v_pk_fma_f32 v[2:3], v[96:97], v[64:65], v[2:3] op_sel:[0,1,0]
	v_pk_fma_f32 v[4:5], v[98:99], v[64:65], v[4:5] op_sel:[0,1,0]
	s_waitcnt vmcnt(13)
	v_pk_fma_f32 v[14:15], v[100:101], v[54:55], v[14:15] op_sel_hi:[1,0,1]
	v_pk_fma_f32 v[16:17], v[102:103], v[54:55], v[16:17] op_sel_hi:[1,0,1]
	v_pk_fma_f32 v[10:11], v[100:101], v[58:59], v[10:11] op_sel_hi:[1,0,1]
	v_pk_fma_f32 v[12:13], v[102:103], v[58:59], v[12:13] op_sel_hi:[1,0,1]
	v_pk_fma_f32 v[6:7], v[100:101], v[62:63], v[6:7] op_sel_hi:[1,0,1]
	v_pk_fma_f32 v[8:9], v[102:103], v[62:63], v[8:9] op_sel_hi:[1,0,1]
	v_pk_fma_f32 v[2:3], v[100:101], v[66:67], v[2:3] op_sel_hi:[1,0,1]
	v_pk_fma_f32 v[4:5], v[102:103], v[66:67], v[4:5] op_sel_hi:[1,0,1]
	s_waitcnt vmcnt(12)
	v_pk_fma_f32 v[14:15], v[104:105], v[68:69], v[14:15] op_sel_hi:[1,0,1]
	v_pk_fma_f32 v[16:17], v[106:107], v[68:69], v[16:17] op_sel_hi:[1,0,1]
	v_pk_fma_f32 v[10:11], v[104:105], v[70:71], v[10:11] op_sel_hi:[1,0,1]
	v_pk_fma_f32 v[12:13], v[106:107], v[70:71], v[12:13] op_sel_hi:[1,0,1]
	v_pk_fma_f32 v[6:7], v[104:105], v[72:73], v[6:7] op_sel_hi:[1,0,1]
	v_pk_fma_f32 v[8:9], v[106:107], v[72:73], v[8:9] op_sel_hi:[1,0,1]
	v_pk_fma_f32 v[2:3], v[104:105], v[74:75], v[2:3] op_sel_hi:[1,0,1]
	v_pk_fma_f32 v[4:5], v[106:107], v[74:75], v[4:5] op_sel_hi:[1,0,1]
	v_lshl_add_u64 v[140:141], v[26:27], 0, v[34:35]
	v_lshl_add_u64 v[142:143], v[26:27], 0, v[32:33]
	v_lshl_add_u64 v[144:145], v[26:27], 0, v[30:31]
	v_lshl_add_u64 v[146:147], v[26:27], 0, v[28:29]
	global_load_dwordx4 v[92:95], v[140:141], off
	global_load_dwordx4 v[96:99], v[142:143], off
	global_load_dwordx4 v[100:103], v[144:145], off
	global_load_dwordx4 v[104:107], v[146:147], off
	v_lshl_add_u64 v[26:27], v[26:27], 0, v[22:23]
	ds_read_b128 v[52:55], v25 offset:32
	ds_read_b128 v[56:59], v25 offset:4128
	ds_read_b128 v[60:63], v25 offset:8224
	ds_read_b128 v[64:67], v25 offset:12320
	s_waitcnt lgkmcnt(0)
	v_mov_b32_e32 v68, v55
	v_mov_b32_e32 v70, v59
	v_mov_b32_e32 v72, v63
	v_mov_b32_e32 v74, v67
	s_waitcnt vmcnt(15)
	v_pk_fma_f32 v[14:15], v[108:109], v[52:53], v[14:15] op_sel_hi:[1,0,1]
	v_pk_fma_f32 v[16:17], v[110:111], v[52:53], v[16:17] op_sel_hi:[1,0,1]
	v_pk_fma_f32 v[10:11], v[108:109], v[56:57], v[10:11] op_sel_hi:[1,0,1]
	v_pk_fma_f32 v[12:13], v[110:111], v[56:57], v[12:13] op_sel_hi:[1,0,1]
	v_pk_fma_f32 v[6:7], v[108:109], v[60:61], v[6:7] op_sel_hi:[1,0,1]
	v_pk_fma_f32 v[8:9], v[110:111], v[60:61], v[8:9] op_sel_hi:[1,0,1]
	v_pk_fma_f32 v[2:3], v[108:109], v[64:65], v[2:3] op_sel_hi:[1,0,1]
	v_pk_fma_f32 v[4:5], v[110:111], v[64:65], v[4:5] op_sel_hi:[1,0,1]
	s_waitcnt vmcnt(14)
	v_pk_fma_f32 v[14:15], v[112:113], v[52:53], v[14:15] op_sel:[0,1,0]
	v_pk_fma_f32 v[16:17], v[114:115], v[52:53], v[16:17] op_sel:[0,1,0]
	v_pk_fma_f32 v[10:11], v[112:113], v[56:57], v[10:11] op_sel:[0,1,0]
	v_pk_fma_f32 v[12:13], v[114:115], v[56:57], v[12:13] op_sel:[0,1,0]
	v_pk_fma_f32 v[6:7], v[112:113], v[60:61], v[6:7] op_sel:[0,1,0]
	v_pk_fma_f32 v[8:9], v[114:115], v[60:61], v[8:9] op_sel:[0,1,0]
	v_pk_fma_f32 v[2:3], v[112:113], v[64:65], v[2:3] op_sel:[0,1,0]
	v_pk_fma_f32 v[4:5], v[114:115], v[64:65], v[4:5] op_sel:[0,1,0]
	s_waitcnt vmcnt(13)
	v_pk_fma_f32 v[14:15], v[116:117], v[54:55], v[14:15] op_sel_hi:[1,0,1]
	v_pk_fma_f32 v[16:17], v[118:119], v[54:55], v[16:17] op_sel_hi:[1,0,1]
	v_pk_fma_f32 v[10:11], v[116:117], v[58:59], v[10:11] op_sel_hi:[1,0,1]
	v_pk_fma_f32 v[12:13], v[118:119], v[58:59], v[12:13] op_sel_hi:[1,0,1]
	v_pk_fma_f32 v[6:7], v[116:117], v[62:63], v[6:7] op_sel_hi:[1,0,1]
	v_pk_fma_f32 v[8:9], v[118:119], v[62:63], v[8:9] op_sel_hi:[1,0,1]
	v_pk_fma_f32 v[2:3], v[116:117], v[66:67], v[2:3] op_sel_hi:[1,0,1]
	v_pk_fma_f32 v[4:5], v[118:119], v[66:67], v[4:5] op_sel_hi:[1,0,1]
	s_waitcnt vmcnt(12)
	v_pk_fma_f32 v[14:15], v[120:121], v[68:69], v[14:15] op_sel_hi:[1,0,1]
	v_pk_fma_f32 v[16:17], v[122:123], v[68:69], v[16:17] op_sel_hi:[1,0,1]
	v_pk_fma_f32 v[10:11], v[120:121], v[70:71], v[10:11] op_sel_hi:[1,0,1]
	v_pk_fma_f32 v[12:13], v[122:123], v[70:71], v[12:13] op_sel_hi:[1,0,1]
	v_pk_fma_f32 v[6:7], v[120:121], v[72:73], v[6:7] op_sel_hi:[1,0,1]
	v_pk_fma_f32 v[8:9], v[122:123], v[72:73], v[8:9] op_sel_hi:[1,0,1]
	v_pk_fma_f32 v[2:3], v[120:121], v[74:75], v[2:3] op_sel_hi:[1,0,1]
	v_pk_fma_f32 v[4:5], v[122:123], v[74:75], v[4:5] op_sel_hi:[1,0,1]
	v_lshl_add_u64 v[140:141], v[26:27], 0, v[34:35]
	v_lshl_add_u64 v[142:143], v[26:27], 0, v[32:33]
	v_lshl_add_u64 v[144:145], v[26:27], 0, v[30:31]
	v_lshl_add_u64 v[146:147], v[26:27], 0, v[28:29]
	global_load_dwordx4 v[108:111], v[140:141], off
	global_load_dwordx4 v[112:115], v[142:143], off
	global_load_dwordx4 v[116:119], v[144:145], off
	global_load_dwordx4 v[120:123], v[146:147], off
	v_lshl_add_u64 v[26:27], v[26:27], 0, v[22:23]
	ds_read_b128 v[52:55], v25 offset:48
	ds_read_b128 v[56:59], v25 offset:4144
	ds_read_b128 v[60:63], v25 offset:8240
	ds_read_b128 v[64:67], v25 offset:12336
	s_waitcnt lgkmcnt(0)
	v_mov_b32_e32 v68, v55
	v_mov_b32_e32 v70, v59
	v_mov_b32_e32 v72, v63
	v_mov_b32_e32 v74, v67
	s_waitcnt vmcnt(15)
	v_pk_fma_f32 v[14:15], v[124:125], v[52:53], v[14:15] op_sel_hi:[1,0,1]
	v_pk_fma_f32 v[16:17], v[126:127], v[52:53], v[16:17] op_sel_hi:[1,0,1]
	v_pk_fma_f32 v[10:11], v[124:125], v[56:57], v[10:11] op_sel_hi:[1,0,1]
	v_pk_fma_f32 v[12:13], v[126:127], v[56:57], v[12:13] op_sel_hi:[1,0,1]
	v_pk_fma_f32 v[6:7], v[124:125], v[60:61], v[6:7] op_sel_hi:[1,0,1]
	v_pk_fma_f32 v[8:9], v[126:127], v[60:61], v[8:9] op_sel_hi:[1,0,1]
	v_pk_fma_f32 v[2:3], v[124:125], v[64:65], v[2:3] op_sel_hi:[1,0,1]
	v_pk_fma_f32 v[4:5], v[126:127], v[64:65], v[4:5] op_sel_hi:[1,0,1]
	s_waitcnt vmcnt(14)
	v_pk_fma_f32 v[14:15], v[128:129], v[52:53], v[14:15] op_sel:[0,1,0]
	v_pk_fma_f32 v[16:17], v[130:131], v[52:53], v[16:17] op_sel:[0,1,0]
	v_pk_fma_f32 v[10:11], v[128:129], v[56:57], v[10:11] op_sel:[0,1,0]
	v_pk_fma_f32 v[12:13], v[130:131], v[56:57], v[12:13] op_sel:[0,1,0]
	v_pk_fma_f32 v[6:7], v[128:129], v[60:61], v[6:7] op_sel:[0,1,0]
	v_pk_fma_f32 v[8:9], v[130:131], v[60:61], v[8:9] op_sel:[0,1,0]
	v_pk_fma_f32 v[2:3], v[128:129], v[64:65], v[2:3] op_sel:[0,1,0]
	v_pk_fma_f32 v[4:5], v[130:131], v[64:65], v[4:5] op_sel:[0,1,0]
	s_waitcnt vmcnt(13)
	v_pk_fma_f32 v[14:15], v[132:133], v[54:55], v[14:15] op_sel_hi:[1,0,1]
	v_pk_fma_f32 v[16:17], v[134:135], v[54:55], v[16:17] op_sel_hi:[1,0,1]
	v_pk_fma_f32 v[10:11], v[132:133], v[58:59], v[10:11] op_sel_hi:[1,0,1]
	v_pk_fma_f32 v[12:13], v[134:135], v[58:59], v[12:13] op_sel_hi:[1,0,1]
	v_pk_fma_f32 v[6:7], v[132:133], v[62:63], v[6:7] op_sel_hi:[1,0,1]
	v_pk_fma_f32 v[8:9], v[134:135], v[62:63], v[8:9] op_sel_hi:[1,0,1]
	v_pk_fma_f32 v[2:3], v[132:133], v[66:67], v[2:3] op_sel_hi:[1,0,1]
	v_pk_fma_f32 v[4:5], v[134:135], v[66:67], v[4:5] op_sel_hi:[1,0,1]
	s_waitcnt vmcnt(12)
	v_pk_fma_f32 v[14:15], v[136:137], v[68:69], v[14:15] op_sel_hi:[1,0,1]
	v_pk_fma_f32 v[16:17], v[138:139], v[68:69], v[16:17] op_sel_hi:[1,0,1]
	v_pk_fma_f32 v[10:11], v[136:137], v[70:71], v[10:11] op_sel_hi:[1,0,1]
	v_pk_fma_f32 v[12:13], v[138:139], v[70:71], v[12:13] op_sel_hi:[1,0,1]
	v_pk_fma_f32 v[6:7], v[136:137], v[72:73], v[6:7] op_sel_hi:[1,0,1]
	v_pk_fma_f32 v[8:9], v[138:139], v[72:73], v[8:9] op_sel_hi:[1,0,1]
	v_pk_fma_f32 v[2:3], v[136:137], v[74:75], v[2:3] op_sel_hi:[1,0,1]
	v_pk_fma_f32 v[4:5], v[138:139], v[74:75], v[4:5] op_sel_hi:[1,0,1]
	v_lshl_add_u64 v[140:141], v[26:27], 0, v[34:35]
	v_lshl_add_u64 v[142:143], v[26:27], 0, v[32:33]
	v_lshl_add_u64 v[144:145], v[26:27], 0, v[30:31]
	v_lshl_add_u64 v[146:147], v[26:27], 0, v[28:29]
	global_load_dwordx4 v[124:127], v[140:141], off
	global_load_dwordx4 v[128:131], v[142:143], off
	global_load_dwordx4 v[132:135], v[144:145], off
	global_load_dwordx4 v[136:139], v[146:147], off
	v_lshl_add_u64 v[26:27], v[26:27], 0, v[22:23]
	ds_read_b128 v[52:55], v25 offset:64
	ds_read_b128 v[56:59], v25 offset:4160
	ds_read_b128 v[60:63], v25 offset:8256
	ds_read_b128 v[64:67], v25 offset:12352
	s_waitcnt lgkmcnt(0)
	v_mov_b32_e32 v68, v55
	v_mov_b32_e32 v70, v59
	v_mov_b32_e32 v72, v63
	v_mov_b32_e32 v74, v67
	s_waitcnt vmcnt(15)
	v_pk_fma_f32 v[14:15], v[76:77], v[52:53], v[14:15] op_sel_hi:[1,0,1]
	v_pk_fma_f32 v[16:17], v[78:79], v[52:53], v[16:17] op_sel_hi:[1,0,1]
	v_pk_fma_f32 v[10:11], v[76:77], v[56:57], v[10:11] op_sel_hi:[1,0,1]
	v_pk_fma_f32 v[12:13], v[78:79], v[56:57], v[12:13] op_sel_hi:[1,0,1]
	v_pk_fma_f32 v[6:7], v[76:77], v[60:61], v[6:7] op_sel_hi:[1,0,1]
	v_pk_fma_f32 v[8:9], v[78:79], v[60:61], v[8:9] op_sel_hi:[1,0,1]
	v_pk_fma_f32 v[2:3], v[76:77], v[64:65], v[2:3] op_sel_hi:[1,0,1]
	v_pk_fma_f32 v[4:5], v[78:79], v[64:65], v[4:5] op_sel_hi:[1,0,1]
	s_waitcnt vmcnt(14)
	v_pk_fma_f32 v[14:15], v[80:81], v[52:53], v[14:15] op_sel:[0,1,0]
	v_pk_fma_f32 v[16:17], v[82:83], v[52:53], v[16:17] op_sel:[0,1,0]
	v_pk_fma_f32 v[10:11], v[80:81], v[56:57], v[10:11] op_sel:[0,1,0]
	v_pk_fma_f32 v[12:13], v[82:83], v[56:57], v[12:13] op_sel:[0,1,0]
	v_pk_fma_f32 v[6:7], v[80:81], v[60:61], v[6:7] op_sel:[0,1,0]
	v_pk_fma_f32 v[8:9], v[82:83], v[60:61], v[8:9] op_sel:[0,1,0]
	v_pk_fma_f32 v[2:3], v[80:81], v[64:65], v[2:3] op_sel:[0,1,0]
	v_pk_fma_f32 v[4:5], v[82:83], v[64:65], v[4:5] op_sel:[0,1,0]
	s_waitcnt vmcnt(13)
	v_pk_fma_f32 v[14:15], v[84:85], v[54:55], v[14:15] op_sel_hi:[1,0,1]
	v_pk_fma_f32 v[16:17], v[86:87], v[54:55], v[16:17] op_sel_hi:[1,0,1]
	v_pk_fma_f32 v[10:11], v[84:85], v[58:59], v[10:11] op_sel_hi:[1,0,1]
	v_pk_fma_f32 v[12:13], v[86:87], v[58:59], v[12:13] op_sel_hi:[1,0,1]
	v_pk_fma_f32 v[6:7], v[84:85], v[62:63], v[6:7] op_sel_hi:[1,0,1]
	v_pk_fma_f32 v[8:9], v[86:87], v[62:63], v[8:9] op_sel_hi:[1,0,1]
	v_pk_fma_f32 v[2:3], v[84:85], v[66:67], v[2:3] op_sel_hi:[1,0,1]
	v_pk_fma_f32 v[4:5], v[86:87], v[66:67], v[4:5] op_sel_hi:[1,0,1]
	s_waitcnt vmcnt(12)
	v_pk_fma_f32 v[14:15], v[88:89], v[68:69], v[14:15] op_sel_hi:[1,0,1]
	v_pk_fma_f32 v[16:17], v[90:91], v[68:69], v[16:17] op_sel_hi:[1,0,1]
	v_pk_fma_f32 v[10:11], v[88:89], v[70:71], v[10:11] op_sel_hi:[1,0,1]
	v_pk_fma_f32 v[12:13], v[90:91], v[70:71], v[12:13] op_sel_hi:[1,0,1]
	v_pk_fma_f32 v[6:7], v[88:89], v[72:73], v[6:7] op_sel_hi:[1,0,1]
	v_pk_fma_f32 v[8:9], v[90:91], v[72:73], v[8:9] op_sel_hi:[1,0,1]
	v_pk_fma_f32 v[2:3], v[88:89], v[74:75], v[2:3] op_sel_hi:[1,0,1]
	v_pk_fma_f32 v[4:5], v[90:91], v[74:75], v[4:5] op_sel_hi:[1,0,1]
	v_lshl_add_u64 v[140:141], v[26:27], 0, v[34:35]
	v_lshl_add_u64 v[142:143], v[26:27], 0, v[32:33]
	v_lshl_add_u64 v[144:145], v[26:27], 0, v[30:31]
	v_lshl_add_u64 v[146:147], v[26:27], 0, v[28:29]
	global_load_dwordx4 v[76:79], v[140:141], off
	global_load_dwordx4 v[80:83], v[142:143], off
	global_load_dwordx4 v[84:87], v[144:145], off
	global_load_dwordx4 v[88:91], v[146:147], off
	v_lshl_add_u64 v[26:27], v[26:27], 0, v[22:23]
	ds_read_b128 v[52:55], v25 offset:80
	ds_read_b128 v[56:59], v25 offset:4176
	ds_read_b128 v[60:63], v25 offset:8272
	ds_read_b128 v[64:67], v25 offset:12368
	s_waitcnt lgkmcnt(0)
	v_mov_b32_e32 v68, v55
	v_mov_b32_e32 v70, v59
	v_mov_b32_e32 v72, v63
	v_mov_b32_e32 v74, v67
	s_waitcnt vmcnt(15)
	v_pk_fma_f32 v[14:15], v[92:93], v[52:53], v[14:15] op_sel_hi:[1,0,1]
	v_pk_fma_f32 v[16:17], v[94:95], v[52:53], v[16:17] op_sel_hi:[1,0,1]
	v_pk_fma_f32 v[10:11], v[92:93], v[56:57], v[10:11] op_sel_hi:[1,0,1]
	v_pk_fma_f32 v[12:13], v[94:95], v[56:57], v[12:13] op_sel_hi:[1,0,1]
	v_pk_fma_f32 v[6:7], v[92:93], v[60:61], v[6:7] op_sel_hi:[1,0,1]
	v_pk_fma_f32 v[8:9], v[94:95], v[60:61], v[8:9] op_sel_hi:[1,0,1]
	v_pk_fma_f32 v[2:3], v[92:93], v[64:65], v[2:3] op_sel_hi:[1,0,1]
	v_pk_fma_f32 v[4:5], v[94:95], v[64:65], v[4:5] op_sel_hi:[1,0,1]
	s_waitcnt vmcnt(14)
	v_pk_fma_f32 v[14:15], v[96:97], v[52:53], v[14:15] op_sel:[0,1,0]
	v_pk_fma_f32 v[16:17], v[98:99], v[52:53], v[16:17] op_sel:[0,1,0]
	v_pk_fma_f32 v[10:11], v[96:97], v[56:57], v[10:11] op_sel:[0,1,0]
	v_pk_fma_f32 v[12:13], v[98:99], v[56:57], v[12:13] op_sel:[0,1,0]
	v_pk_fma_f32 v[6:7], v[96:97], v[60:61], v[6:7] op_sel:[0,1,0]
	v_pk_fma_f32 v[8:9], v[98:99], v[60:61], v[8:9] op_sel:[0,1,0]
	v_pk_fma_f32 v[2:3], v[96:97], v[64:65], v[2:3] op_sel:[0,1,0]
	v_pk_fma_f32 v[4:5], v[98:99], v[64:65], v[4:5] op_sel:[0,1,0]
	s_waitcnt vmcnt(13)
	v_pk_fma_f32 v[14:15], v[100:101], v[54:55], v[14:15] op_sel_hi:[1,0,1]
	v_pk_fma_f32 v[16:17], v[102:103], v[54:55], v[16:17] op_sel_hi:[1,0,1]
	v_pk_fma_f32 v[10:11], v[100:101], v[58:59], v[10:11] op_sel_hi:[1,0,1]
	v_pk_fma_f32 v[12:13], v[102:103], v[58:59], v[12:13] op_sel_hi:[1,0,1]
	v_pk_fma_f32 v[6:7], v[100:101], v[62:63], v[6:7] op_sel_hi:[1,0,1]
	v_pk_fma_f32 v[8:9], v[102:103], v[62:63], v[8:9] op_sel_hi:[1,0,1]
	v_pk_fma_f32 v[2:3], v[100:101], v[66:67], v[2:3] op_sel_hi:[1,0,1]
	v_pk_fma_f32 v[4:5], v[102:103], v[66:67], v[4:5] op_sel_hi:[1,0,1]
	s_waitcnt vmcnt(12)
	v_pk_fma_f32 v[14:15], v[104:105], v[68:69], v[14:15] op_sel_hi:[1,0,1]
	v_pk_fma_f32 v[16:17], v[106:107], v[68:69], v[16:17] op_sel_hi:[1,0,1]
	v_pk_fma_f32 v[10:11], v[104:105], v[70:71], v[10:11] op_sel_hi:[1,0,1]
	v_pk_fma_f32 v[12:13], v[106:107], v[70:71], v[12:13] op_sel_hi:[1,0,1]
	v_pk_fma_f32 v[6:7], v[104:105], v[72:73], v[6:7] op_sel_hi:[1,0,1]
	v_pk_fma_f32 v[8:9], v[106:107], v[72:73], v[8:9] op_sel_hi:[1,0,1]
	v_pk_fma_f32 v[2:3], v[104:105], v[74:75], v[2:3] op_sel_hi:[1,0,1]
	v_pk_fma_f32 v[4:5], v[106:107], v[74:75], v[4:5] op_sel_hi:[1,0,1]
	v_lshl_add_u64 v[140:141], v[26:27], 0, v[34:35]
	v_lshl_add_u64 v[142:143], v[26:27], 0, v[32:33]
	v_lshl_add_u64 v[144:145], v[26:27], 0, v[30:31]
	v_lshl_add_u64 v[146:147], v[26:27], 0, v[28:29]
	global_load_dwordx4 v[92:95], v[140:141], off
	global_load_dwordx4 v[96:99], v[142:143], off
	global_load_dwordx4 v[100:103], v[144:145], off
	global_load_dwordx4 v[104:107], v[146:147], off
	v_lshl_add_u64 v[26:27], v[26:27], 0, v[22:23]
	ds_read_b128 v[52:55], v25 offset:96
	ds_read_b128 v[56:59], v25 offset:4192
	ds_read_b128 v[60:63], v25 offset:8288
	ds_read_b128 v[64:67], v25 offset:12384
	s_waitcnt lgkmcnt(0)
	v_mov_b32_e32 v68, v55
	v_mov_b32_e32 v70, v59
	v_mov_b32_e32 v72, v63
	v_mov_b32_e32 v74, v67
	s_waitcnt vmcnt(15)
	v_pk_fma_f32 v[14:15], v[108:109], v[52:53], v[14:15] op_sel_hi:[1,0,1]
	v_pk_fma_f32 v[16:17], v[110:111], v[52:53], v[16:17] op_sel_hi:[1,0,1]
	v_pk_fma_f32 v[10:11], v[108:109], v[56:57], v[10:11] op_sel_hi:[1,0,1]
	v_pk_fma_f32 v[12:13], v[110:111], v[56:57], v[12:13] op_sel_hi:[1,0,1]
	v_pk_fma_f32 v[6:7], v[108:109], v[60:61], v[6:7] op_sel_hi:[1,0,1]
	v_pk_fma_f32 v[8:9], v[110:111], v[60:61], v[8:9] op_sel_hi:[1,0,1]
	v_pk_fma_f32 v[2:3], v[108:109], v[64:65], v[2:3] op_sel_hi:[1,0,1]
	v_pk_fma_f32 v[4:5], v[110:111], v[64:65], v[4:5] op_sel_hi:[1,0,1]
	s_waitcnt vmcnt(14)
	v_pk_fma_f32 v[14:15], v[112:113], v[52:53], v[14:15] op_sel:[0,1,0]
	v_pk_fma_f32 v[16:17], v[114:115], v[52:53], v[16:17] op_sel:[0,1,0]
	v_pk_fma_f32 v[10:11], v[112:113], v[56:57], v[10:11] op_sel:[0,1,0]
	v_pk_fma_f32 v[12:13], v[114:115], v[56:57], v[12:13] op_sel:[0,1,0]
	v_pk_fma_f32 v[6:7], v[112:113], v[60:61], v[6:7] op_sel:[0,1,0]
	v_pk_fma_f32 v[8:9], v[114:115], v[60:61], v[8:9] op_sel:[0,1,0]
	v_pk_fma_f32 v[2:3], v[112:113], v[64:65], v[2:3] op_sel:[0,1,0]
	v_pk_fma_f32 v[4:5], v[114:115], v[64:65], v[4:5] op_sel:[0,1,0]
	s_waitcnt vmcnt(13)
	v_pk_fma_f32 v[14:15], v[116:117], v[54:55], v[14:15] op_sel_hi:[1,0,1]
	v_pk_fma_f32 v[16:17], v[118:119], v[54:55], v[16:17] op_sel_hi:[1,0,1]
	v_pk_fma_f32 v[10:11], v[116:117], v[58:59], v[10:11] op_sel_hi:[1,0,1]
	v_pk_fma_f32 v[12:13], v[118:119], v[58:59], v[12:13] op_sel_hi:[1,0,1]
	v_pk_fma_f32 v[6:7], v[116:117], v[62:63], v[6:7] op_sel_hi:[1,0,1]
	v_pk_fma_f32 v[8:9], v[118:119], v[62:63], v[8:9] op_sel_hi:[1,0,1]
	v_pk_fma_f32 v[2:3], v[116:117], v[66:67], v[2:3] op_sel_hi:[1,0,1]
	v_pk_fma_f32 v[4:5], v[118:119], v[66:67], v[4:5] op_sel_hi:[1,0,1]
	s_waitcnt vmcnt(12)
	v_pk_fma_f32 v[14:15], v[120:121], v[68:69], v[14:15] op_sel_hi:[1,0,1]
	v_pk_fma_f32 v[16:17], v[122:123], v[68:69], v[16:17] op_sel_hi:[1,0,1]
	v_pk_fma_f32 v[10:11], v[120:121], v[70:71], v[10:11] op_sel_hi:[1,0,1]
	v_pk_fma_f32 v[12:13], v[122:123], v[70:71], v[12:13] op_sel_hi:[1,0,1]
	v_pk_fma_f32 v[6:7], v[120:121], v[72:73], v[6:7] op_sel_hi:[1,0,1]
	v_pk_fma_f32 v[8:9], v[122:123], v[72:73], v[8:9] op_sel_hi:[1,0,1]
	v_pk_fma_f32 v[2:3], v[120:121], v[74:75], v[2:3] op_sel_hi:[1,0,1]
	v_pk_fma_f32 v[4:5], v[122:123], v[74:75], v[4:5] op_sel_hi:[1,0,1]
	v_lshl_add_u64 v[140:141], v[26:27], 0, v[34:35]
	v_lshl_add_u64 v[142:143], v[26:27], 0, v[32:33]
	v_lshl_add_u64 v[144:145], v[26:27], 0, v[30:31]
	v_lshl_add_u64 v[146:147], v[26:27], 0, v[28:29]
	global_load_dwordx4 v[108:111], v[140:141], off
	global_load_dwordx4 v[112:115], v[142:143], off
	global_load_dwordx4 v[116:119], v[144:145], off
	global_load_dwordx4 v[120:123], v[146:147], off
	v_lshl_add_u64 v[26:27], v[26:27], 0, v[22:23]
	ds_read_b128 v[52:55], v25 offset:112
	ds_read_b128 v[56:59], v25 offset:4208
	ds_read_b128 v[60:63], v25 offset:8304
	ds_read_b128 v[64:67], v25 offset:12400
	s_waitcnt lgkmcnt(0)
	v_mov_b32_e32 v68, v55
	v_mov_b32_e32 v70, v59
	v_mov_b32_e32 v72, v63
	v_mov_b32_e32 v74, v67
	s_waitcnt vmcnt(15)
	v_pk_fma_f32 v[14:15], v[124:125], v[52:53], v[14:15] op_sel_hi:[1,0,1]
	v_pk_fma_f32 v[16:17], v[126:127], v[52:53], v[16:17] op_sel_hi:[1,0,1]
	v_pk_fma_f32 v[10:11], v[124:125], v[56:57], v[10:11] op_sel_hi:[1,0,1]
	v_pk_fma_f32 v[12:13], v[126:127], v[56:57], v[12:13] op_sel_hi:[1,0,1]
	v_pk_fma_f32 v[6:7], v[124:125], v[60:61], v[6:7] op_sel_hi:[1,0,1]
	v_pk_fma_f32 v[8:9], v[126:127], v[60:61], v[8:9] op_sel_hi:[1,0,1]
	v_pk_fma_f32 v[2:3], v[124:125], v[64:65], v[2:3] op_sel_hi:[1,0,1]
	v_pk_fma_f32 v[4:5], v[126:127], v[64:65], v[4:5] op_sel_hi:[1,0,1]
	s_waitcnt vmcnt(14)
	v_pk_fma_f32 v[14:15], v[128:129], v[52:53], v[14:15] op_sel:[0,1,0]
	v_pk_fma_f32 v[16:17], v[130:131], v[52:53], v[16:17] op_sel:[0,1,0]
	v_pk_fma_f32 v[10:11], v[128:129], v[56:57], v[10:11] op_sel:[0,1,0]
	v_pk_fma_f32 v[12:13], v[130:131], v[56:57], v[12:13] op_sel:[0,1,0]
	v_pk_fma_f32 v[6:7], v[128:129], v[60:61], v[6:7] op_sel:[0,1,0]
	v_pk_fma_f32 v[8:9], v[130:131], v[60:61], v[8:9] op_sel:[0,1,0]
	v_pk_fma_f32 v[2:3], v[128:129], v[64:65], v[2:3] op_sel:[0,1,0]
	v_pk_fma_f32 v[4:5], v[130:131], v[64:65], v[4:5] op_sel:[0,1,0]
	s_waitcnt vmcnt(13)
	v_pk_fma_f32 v[14:15], v[132:133], v[54:55], v[14:15] op_sel_hi:[1,0,1]
	v_pk_fma_f32 v[16:17], v[134:135], v[54:55], v[16:17] op_sel_hi:[1,0,1]
	v_pk_fma_f32 v[10:11], v[132:133], v[58:59], v[10:11] op_sel_hi:[1,0,1]
	v_pk_fma_f32 v[12:13], v[134:135], v[58:59], v[12:13] op_sel_hi:[1,0,1]
	v_pk_fma_f32 v[6:7], v[132:133], v[62:63], v[6:7] op_sel_hi:[1,0,1]
	v_pk_fma_f32 v[8:9], v[134:135], v[62:63], v[8:9] op_sel_hi:[1,0,1]
	v_pk_fma_f32 v[2:3], v[132:133], v[66:67], v[2:3] op_sel_hi:[1,0,1]
	v_pk_fma_f32 v[4:5], v[134:135], v[66:67], v[4:5] op_sel_hi:[1,0,1]
	s_waitcnt vmcnt(12)
	v_pk_fma_f32 v[14:15], v[136:137], v[68:69], v[14:15] op_sel_hi:[1,0,1]
	v_pk_fma_f32 v[16:17], v[138:139], v[68:69], v[16:17] op_sel_hi:[1,0,1]
	v_pk_fma_f32 v[10:11], v[136:137], v[70:71], v[10:11] op_sel_hi:[1,0,1]
	v_pk_fma_f32 v[12:13], v[138:139], v[70:71], v[12:13] op_sel_hi:[1,0,1]
	v_pk_fma_f32 v[6:7], v[136:137], v[72:73], v[6:7] op_sel_hi:[1,0,1]
	v_pk_fma_f32 v[8:9], v[138:139], v[72:73], v[8:9] op_sel_hi:[1,0,1]
	v_pk_fma_f32 v[2:3], v[136:137], v[74:75], v[2:3] op_sel_hi:[1,0,1]
	v_pk_fma_f32 v[4:5], v[138:139], v[74:75], v[4:5] op_sel_hi:[1,0,1]
	v_lshl_add_u64 v[140:141], v[26:27], 0, v[34:35]
	v_lshl_add_u64 v[142:143], v[26:27], 0, v[32:33]
	v_lshl_add_u64 v[144:145], v[26:27], 0, v[30:31]
	v_lshl_add_u64 v[146:147], v[26:27], 0, v[28:29]
	global_load_dwordx4 v[124:127], v[140:141], off
	global_load_dwordx4 v[128:131], v[142:143], off
	global_load_dwordx4 v[132:135], v[144:145], off
	global_load_dwordx4 v[136:139], v[146:147], off
	v_lshl_add_u64 v[26:27], v[26:27], 0, v[22:23]
	ds_read_b128 v[52:55], v25 offset:128
	ds_read_b128 v[56:59], v25 offset:4224
	ds_read_b128 v[60:63], v25 offset:8320
	ds_read_b128 v[64:67], v25 offset:12416
	s_waitcnt lgkmcnt(0)
	v_mov_b32_e32 v68, v55
	v_mov_b32_e32 v70, v59
	v_mov_b32_e32 v72, v63
	v_mov_b32_e32 v74, v67
	s_waitcnt vmcnt(15)
	v_pk_fma_f32 v[14:15], v[76:77], v[52:53], v[14:15] op_sel_hi:[1,0,1]
	v_pk_fma_f32 v[16:17], v[78:79], v[52:53], v[16:17] op_sel_hi:[1,0,1]
	v_pk_fma_f32 v[10:11], v[76:77], v[56:57], v[10:11] op_sel_hi:[1,0,1]
	v_pk_fma_f32 v[12:13], v[78:79], v[56:57], v[12:13] op_sel_hi:[1,0,1]
	v_pk_fma_f32 v[6:7], v[76:77], v[60:61], v[6:7] op_sel_hi:[1,0,1]
	v_pk_fma_f32 v[8:9], v[78:79], v[60:61], v[8:9] op_sel_hi:[1,0,1]
	v_pk_fma_f32 v[2:3], v[76:77], v[64:65], v[2:3] op_sel_hi:[1,0,1]
	v_pk_fma_f32 v[4:5], v[78:79], v[64:65], v[4:5] op_sel_hi:[1,0,1]
	s_waitcnt vmcnt(14)
	v_pk_fma_f32 v[14:15], v[80:81], v[52:53], v[14:15] op_sel:[0,1,0]
	v_pk_fma_f32 v[16:17], v[82:83], v[52:53], v[16:17] op_sel:[0,1,0]
	v_pk_fma_f32 v[10:11], v[80:81], v[56:57], v[10:11] op_sel:[0,1,0]
	v_pk_fma_f32 v[12:13], v[82:83], v[56:57], v[12:13] op_sel:[0,1,0]
	v_pk_fma_f32 v[6:7], v[80:81], v[60:61], v[6:7] op_sel:[0,1,0]
	v_pk_fma_f32 v[8:9], v[82:83], v[60:61], v[8:9] op_sel:[0,1,0]
	v_pk_fma_f32 v[2:3], v[80:81], v[64:65], v[2:3] op_sel:[0,1,0]
	v_pk_fma_f32 v[4:5], v[82:83], v[64:65], v[4:5] op_sel:[0,1,0]
	s_waitcnt vmcnt(13)
	v_pk_fma_f32 v[14:15], v[84:85], v[54:55], v[14:15] op_sel_hi:[1,0,1]
	v_pk_fma_f32 v[16:17], v[86:87], v[54:55], v[16:17] op_sel_hi:[1,0,1]
	v_pk_fma_f32 v[10:11], v[84:85], v[58:59], v[10:11] op_sel_hi:[1,0,1]
	v_pk_fma_f32 v[12:13], v[86:87], v[58:59], v[12:13] op_sel_hi:[1,0,1]
	v_pk_fma_f32 v[6:7], v[84:85], v[62:63], v[6:7] op_sel_hi:[1,0,1]
	v_pk_fma_f32 v[8:9], v[86:87], v[62:63], v[8:9] op_sel_hi:[1,0,1]
	v_pk_fma_f32 v[2:3], v[84:85], v[66:67], v[2:3] op_sel_hi:[1,0,1]
	v_pk_fma_f32 v[4:5], v[86:87], v[66:67], v[4:5] op_sel_hi:[1,0,1]
	s_waitcnt vmcnt(12)
	v_pk_fma_f32 v[14:15], v[88:89], v[68:69], v[14:15] op_sel_hi:[1,0,1]
	v_pk_fma_f32 v[16:17], v[90:91], v[68:69], v[16:17] op_sel_hi:[1,0,1]
	v_pk_fma_f32 v[10:11], v[88:89], v[70:71], v[10:11] op_sel_hi:[1,0,1]
	v_pk_fma_f32 v[12:13], v[90:91], v[70:71], v[12:13] op_sel_hi:[1,0,1]
	v_pk_fma_f32 v[6:7], v[88:89], v[72:73], v[6:7] op_sel_hi:[1,0,1]
	v_pk_fma_f32 v[8:9], v[90:91], v[72:73], v[8:9] op_sel_hi:[1,0,1]
	v_pk_fma_f32 v[2:3], v[88:89], v[74:75], v[2:3] op_sel_hi:[1,0,1]
	v_pk_fma_f32 v[4:5], v[90:91], v[74:75], v[4:5] op_sel_hi:[1,0,1]
	v_lshl_add_u64 v[140:141], v[26:27], 0, v[34:35]
	v_lshl_add_u64 v[142:143], v[26:27], 0, v[32:33]
	v_lshl_add_u64 v[144:145], v[26:27], 0, v[30:31]
	v_lshl_add_u64 v[146:147], v[26:27], 0, v[28:29]
	global_load_dwordx4 v[76:79], v[140:141], off
	global_load_dwordx4 v[80:83], v[142:143], off
	global_load_dwordx4 v[84:87], v[144:145], off
	global_load_dwordx4 v[88:91], v[146:147], off
	v_lshl_add_u64 v[26:27], v[26:27], 0, v[22:23]
	ds_read_b128 v[52:55], v25 offset:144
	ds_read_b128 v[56:59], v25 offset:4240
	ds_read_b128 v[60:63], v25 offset:8336
	ds_read_b128 v[64:67], v25 offset:12432
	s_waitcnt lgkmcnt(0)
	v_mov_b32_e32 v68, v55
	v_mov_b32_e32 v70, v59
	v_mov_b32_e32 v72, v63
	v_mov_b32_e32 v74, v67
	s_waitcnt vmcnt(15)
	v_pk_fma_f32 v[14:15], v[92:93], v[52:53], v[14:15] op_sel_hi:[1,0,1]
	v_pk_fma_f32 v[16:17], v[94:95], v[52:53], v[16:17] op_sel_hi:[1,0,1]
	v_pk_fma_f32 v[10:11], v[92:93], v[56:57], v[10:11] op_sel_hi:[1,0,1]
	v_pk_fma_f32 v[12:13], v[94:95], v[56:57], v[12:13] op_sel_hi:[1,0,1]
	v_pk_fma_f32 v[6:7], v[92:93], v[60:61], v[6:7] op_sel_hi:[1,0,1]
	v_pk_fma_f32 v[8:9], v[94:95], v[60:61], v[8:9] op_sel_hi:[1,0,1]
	v_pk_fma_f32 v[2:3], v[92:93], v[64:65], v[2:3] op_sel_hi:[1,0,1]
	v_pk_fma_f32 v[4:5], v[94:95], v[64:65], v[4:5] op_sel_hi:[1,0,1]
	s_waitcnt vmcnt(14)
	v_pk_fma_f32 v[14:15], v[96:97], v[52:53], v[14:15] op_sel:[0,1,0]
	v_pk_fma_f32 v[16:17], v[98:99], v[52:53], v[16:17] op_sel:[0,1,0]
	v_pk_fma_f32 v[10:11], v[96:97], v[56:57], v[10:11] op_sel:[0,1,0]
	v_pk_fma_f32 v[12:13], v[98:99], v[56:57], v[12:13] op_sel:[0,1,0]
	v_pk_fma_f32 v[6:7], v[96:97], v[60:61], v[6:7] op_sel:[0,1,0]
	v_pk_fma_f32 v[8:9], v[98:99], v[60:61], v[8:9] op_sel:[0,1,0]
	v_pk_fma_f32 v[2:3], v[96:97], v[64:65], v[2:3] op_sel:[0,1,0]
	v_pk_fma_f32 v[4:5], v[98:99], v[64:65], v[4:5] op_sel:[0,1,0]
	s_waitcnt vmcnt(13)
	v_pk_fma_f32 v[14:15], v[100:101], v[54:55], v[14:15] op_sel_hi:[1,0,1]
	v_pk_fma_f32 v[16:17], v[102:103], v[54:55], v[16:17] op_sel_hi:[1,0,1]
	v_pk_fma_f32 v[10:11], v[100:101], v[58:59], v[10:11] op_sel_hi:[1,0,1]
	v_pk_fma_f32 v[12:13], v[102:103], v[58:59], v[12:13] op_sel_hi:[1,0,1]
	v_pk_fma_f32 v[6:7], v[100:101], v[62:63], v[6:7] op_sel_hi:[1,0,1]
	v_pk_fma_f32 v[8:9], v[102:103], v[62:63], v[8:9] op_sel_hi:[1,0,1]
	v_pk_fma_f32 v[2:3], v[100:101], v[66:67], v[2:3] op_sel_hi:[1,0,1]
	v_pk_fma_f32 v[4:5], v[102:103], v[66:67], v[4:5] op_sel_hi:[1,0,1]
	s_waitcnt vmcnt(12)
	v_pk_fma_f32 v[14:15], v[104:105], v[68:69], v[14:15] op_sel_hi:[1,0,1]
	v_pk_fma_f32 v[16:17], v[106:107], v[68:69], v[16:17] op_sel_hi:[1,0,1]
	v_pk_fma_f32 v[10:11], v[104:105], v[70:71], v[10:11] op_sel_hi:[1,0,1]
	v_pk_fma_f32 v[12:13], v[106:107], v[70:71], v[12:13] op_sel_hi:[1,0,1]
	v_pk_fma_f32 v[6:7], v[104:105], v[72:73], v[6:7] op_sel_hi:[1,0,1]
	v_pk_fma_f32 v[8:9], v[106:107], v[72:73], v[8:9] op_sel_hi:[1,0,1]
	v_pk_fma_f32 v[2:3], v[104:105], v[74:75], v[2:3] op_sel_hi:[1,0,1]
	v_pk_fma_f32 v[4:5], v[106:107], v[74:75], v[4:5] op_sel_hi:[1,0,1]
	v_lshl_add_u64 v[140:141], v[26:27], 0, v[34:35]
	v_lshl_add_u64 v[142:143], v[26:27], 0, v[32:33]
	v_lshl_add_u64 v[144:145], v[26:27], 0, v[30:31]
	v_lshl_add_u64 v[146:147], v[26:27], 0, v[28:29]
	global_load_dwordx4 v[92:95], v[140:141], off
	global_load_dwordx4 v[96:99], v[142:143], off
	global_load_dwordx4 v[100:103], v[144:145], off
	global_load_dwordx4 v[104:107], v[146:147], off
	v_lshl_add_u64 v[26:27], v[26:27], 0, v[22:23]
	ds_read_b128 v[52:55], v25 offset:160
	ds_read_b128 v[56:59], v25 offset:4256
	ds_read_b128 v[60:63], v25 offset:8352
	ds_read_b128 v[64:67], v25 offset:12448
	s_waitcnt lgkmcnt(0)
	v_mov_b32_e32 v68, v55
	v_mov_b32_e32 v70, v59
	v_mov_b32_e32 v72, v63
	v_mov_b32_e32 v74, v67
	s_waitcnt vmcnt(15)
	v_pk_fma_f32 v[14:15], v[108:109], v[52:53], v[14:15] op_sel_hi:[1,0,1]
	v_pk_fma_f32 v[16:17], v[110:111], v[52:53], v[16:17] op_sel_hi:[1,0,1]
	v_pk_fma_f32 v[10:11], v[108:109], v[56:57], v[10:11] op_sel_hi:[1,0,1]
	v_pk_fma_f32 v[12:13], v[110:111], v[56:57], v[12:13] op_sel_hi:[1,0,1]
	v_pk_fma_f32 v[6:7], v[108:109], v[60:61], v[6:7] op_sel_hi:[1,0,1]
	v_pk_fma_f32 v[8:9], v[110:111], v[60:61], v[8:9] op_sel_hi:[1,0,1]
	v_pk_fma_f32 v[2:3], v[108:109], v[64:65], v[2:3] op_sel_hi:[1,0,1]
	v_pk_fma_f32 v[4:5], v[110:111], v[64:65], v[4:5] op_sel_hi:[1,0,1]
	s_waitcnt vmcnt(14)
	v_pk_fma_f32 v[14:15], v[112:113], v[52:53], v[14:15] op_sel:[0,1,0]
	v_pk_fma_f32 v[16:17], v[114:115], v[52:53], v[16:17] op_sel:[0,1,0]
	v_pk_fma_f32 v[10:11], v[112:113], v[56:57], v[10:11] op_sel:[0,1,0]
	v_pk_fma_f32 v[12:13], v[114:115], v[56:57], v[12:13] op_sel:[0,1,0]
	v_pk_fma_f32 v[6:7], v[112:113], v[60:61], v[6:7] op_sel:[0,1,0]
	v_pk_fma_f32 v[8:9], v[114:115], v[60:61], v[8:9] op_sel:[0,1,0]
	v_pk_fma_f32 v[2:3], v[112:113], v[64:65], v[2:3] op_sel:[0,1,0]
	v_pk_fma_f32 v[4:5], v[114:115], v[64:65], v[4:5] op_sel:[0,1,0]
	s_waitcnt vmcnt(13)
	v_pk_fma_f32 v[14:15], v[116:117], v[54:55], v[14:15] op_sel_hi:[1,0,1]
	v_pk_fma_f32 v[16:17], v[118:119], v[54:55], v[16:17] op_sel_hi:[1,0,1]
	v_pk_fma_f32 v[10:11], v[116:117], v[58:59], v[10:11] op_sel_hi:[1,0,1]
	v_pk_fma_f32 v[12:13], v[118:119], v[58:59], v[12:13] op_sel_hi:[1,0,1]
	v_pk_fma_f32 v[6:7], v[116:117], v[62:63], v[6:7] op_sel_hi:[1,0,1]
	v_pk_fma_f32 v[8:9], v[118:119], v[62:63], v[8:9] op_sel_hi:[1,0,1]
	v_pk_fma_f32 v[2:3], v[116:117], v[66:67], v[2:3] op_sel_hi:[1,0,1]
	v_pk_fma_f32 v[4:5], v[118:119], v[66:67], v[4:5] op_sel_hi:[1,0,1]
	s_waitcnt vmcnt(12)
	v_pk_fma_f32 v[14:15], v[120:121], v[68:69], v[14:15] op_sel_hi:[1,0,1]
	v_pk_fma_f32 v[16:17], v[122:123], v[68:69], v[16:17] op_sel_hi:[1,0,1]
	v_pk_fma_f32 v[10:11], v[120:121], v[70:71], v[10:11] op_sel_hi:[1,0,1]
	v_pk_fma_f32 v[12:13], v[122:123], v[70:71], v[12:13] op_sel_hi:[1,0,1]
	v_pk_fma_f32 v[6:7], v[120:121], v[72:73], v[6:7] op_sel_hi:[1,0,1]
	v_pk_fma_f32 v[8:9], v[122:123], v[72:73], v[8:9] op_sel_hi:[1,0,1]
	v_pk_fma_f32 v[2:3], v[120:121], v[74:75], v[2:3] op_sel_hi:[1,0,1]
	v_pk_fma_f32 v[4:5], v[122:123], v[74:75], v[4:5] op_sel_hi:[1,0,1]
	v_lshl_add_u64 v[140:141], v[26:27], 0, v[34:35]
	v_lshl_add_u64 v[142:143], v[26:27], 0, v[32:33]
	v_lshl_add_u64 v[144:145], v[26:27], 0, v[30:31]
	v_lshl_add_u64 v[146:147], v[26:27], 0, v[28:29]
	global_load_dwordx4 v[108:111], v[140:141], off
	global_load_dwordx4 v[112:115], v[142:143], off
	global_load_dwordx4 v[116:119], v[144:145], off
	global_load_dwordx4 v[120:123], v[146:147], off
	v_lshl_add_u64 v[26:27], v[26:27], 0, v[22:23]
	ds_read_b128 v[52:55], v25 offset:176
	ds_read_b128 v[56:59], v25 offset:4272
	ds_read_b128 v[60:63], v25 offset:8368
	ds_read_b128 v[64:67], v25 offset:12464
	s_waitcnt lgkmcnt(0)
	v_mov_b32_e32 v68, v55
	v_mov_b32_e32 v70, v59
	v_mov_b32_e32 v72, v63
	v_mov_b32_e32 v74, v67
	s_waitcnt vmcnt(15)
	v_pk_fma_f32 v[14:15], v[124:125], v[52:53], v[14:15] op_sel_hi:[1,0,1]
	v_pk_fma_f32 v[16:17], v[126:127], v[52:53], v[16:17] op_sel_hi:[1,0,1]
	v_pk_fma_f32 v[10:11], v[124:125], v[56:57], v[10:11] op_sel_hi:[1,0,1]
	v_pk_fma_f32 v[12:13], v[126:127], v[56:57], v[12:13] op_sel_hi:[1,0,1]
	v_pk_fma_f32 v[6:7], v[124:125], v[60:61], v[6:7] op_sel_hi:[1,0,1]
	v_pk_fma_f32 v[8:9], v[126:127], v[60:61], v[8:9] op_sel_hi:[1,0,1]
	v_pk_fma_f32 v[2:3], v[124:125], v[64:65], v[2:3] op_sel_hi:[1,0,1]
	v_pk_fma_f32 v[4:5], v[126:127], v[64:65], v[4:5] op_sel_hi:[1,0,1]
	s_waitcnt vmcnt(14)
	v_pk_fma_f32 v[14:15], v[128:129], v[52:53], v[14:15] op_sel:[0,1,0]
	v_pk_fma_f32 v[16:17], v[130:131], v[52:53], v[16:17] op_sel:[0,1,0]
	v_pk_fma_f32 v[10:11], v[128:129], v[56:57], v[10:11] op_sel:[0,1,0]
	v_pk_fma_f32 v[12:13], v[130:131], v[56:57], v[12:13] op_sel:[0,1,0]
	v_pk_fma_f32 v[6:7], v[128:129], v[60:61], v[6:7] op_sel:[0,1,0]
	v_pk_fma_f32 v[8:9], v[130:131], v[60:61], v[8:9] op_sel:[0,1,0]
	v_pk_fma_f32 v[2:3], v[128:129], v[64:65], v[2:3] op_sel:[0,1,0]
	v_pk_fma_f32 v[4:5], v[130:131], v[64:65], v[4:5] op_sel:[0,1,0]
	s_waitcnt vmcnt(13)
	v_pk_fma_f32 v[14:15], v[132:133], v[54:55], v[14:15] op_sel_hi:[1,0,1]
	v_pk_fma_f32 v[16:17], v[134:135], v[54:55], v[16:17] op_sel_hi:[1,0,1]
	v_pk_fma_f32 v[10:11], v[132:133], v[58:59], v[10:11] op_sel_hi:[1,0,1]
	v_pk_fma_f32 v[12:13], v[134:135], v[58:59], v[12:13] op_sel_hi:[1,0,1]
	v_pk_fma_f32 v[6:7], v[132:133], v[62:63], v[6:7] op_sel_hi:[1,0,1]
	v_pk_fma_f32 v[8:9], v[134:135], v[62:63], v[8:9] op_sel_hi:[1,0,1]
	v_pk_fma_f32 v[2:3], v[132:133], v[66:67], v[2:3] op_sel_hi:[1,0,1]
	v_pk_fma_f32 v[4:5], v[134:135], v[66:67], v[4:5] op_sel_hi:[1,0,1]
	s_waitcnt vmcnt(12)
	v_pk_fma_f32 v[14:15], v[136:137], v[68:69], v[14:15] op_sel_hi:[1,0,1]
	v_pk_fma_f32 v[16:17], v[138:139], v[68:69], v[16:17] op_sel_hi:[1,0,1]
	v_pk_fma_f32 v[10:11], v[136:137], v[70:71], v[10:11] op_sel_hi:[1,0,1]
	v_pk_fma_f32 v[12:13], v[138:139], v[70:71], v[12:13] op_sel_hi:[1,0,1]
	v_pk_fma_f32 v[6:7], v[136:137], v[72:73], v[6:7] op_sel_hi:[1,0,1]
	v_pk_fma_f32 v[8:9], v[138:139], v[72:73], v[8:9] op_sel_hi:[1,0,1]
	v_pk_fma_f32 v[2:3], v[136:137], v[74:75], v[2:3] op_sel_hi:[1,0,1]
	v_pk_fma_f32 v[4:5], v[138:139], v[74:75], v[4:5] op_sel_hi:[1,0,1]
	v_lshl_add_u64 v[140:141], v[26:27], 0, v[34:35]
	v_lshl_add_u64 v[142:143], v[26:27], 0, v[32:33]
	v_lshl_add_u64 v[144:145], v[26:27], 0, v[30:31]
	v_lshl_add_u64 v[146:147], v[26:27], 0, v[28:29]
	global_load_dwordx4 v[124:127], v[140:141], off
	global_load_dwordx4 v[128:131], v[142:143], off
	global_load_dwordx4 v[132:135], v[144:145], off
	global_load_dwordx4 v[136:139], v[146:147], off
	v_lshl_add_u64 v[26:27], v[26:27], 0, v[22:23]
	ds_read_b128 v[52:55], v25 offset:192
	ds_read_b128 v[56:59], v25 offset:4288
	ds_read_b128 v[60:63], v25 offset:8384
	ds_read_b128 v[64:67], v25 offset:12480
	s_waitcnt lgkmcnt(0)
	v_mov_b32_e32 v68, v55
	v_mov_b32_e32 v70, v59
	v_mov_b32_e32 v72, v63
	v_mov_b32_e32 v74, v67
	s_waitcnt vmcnt(15)
	v_pk_fma_f32 v[14:15], v[76:77], v[52:53], v[14:15] op_sel_hi:[1,0,1]
	v_pk_fma_f32 v[16:17], v[78:79], v[52:53], v[16:17] op_sel_hi:[1,0,1]
	v_pk_fma_f32 v[10:11], v[76:77], v[56:57], v[10:11] op_sel_hi:[1,0,1]
	v_pk_fma_f32 v[12:13], v[78:79], v[56:57], v[12:13] op_sel_hi:[1,0,1]
	v_pk_fma_f32 v[6:7], v[76:77], v[60:61], v[6:7] op_sel_hi:[1,0,1]
	v_pk_fma_f32 v[8:9], v[78:79], v[60:61], v[8:9] op_sel_hi:[1,0,1]
	v_pk_fma_f32 v[2:3], v[76:77], v[64:65], v[2:3] op_sel_hi:[1,0,1]
	v_pk_fma_f32 v[4:5], v[78:79], v[64:65], v[4:5] op_sel_hi:[1,0,1]
	s_waitcnt vmcnt(14)
	v_pk_fma_f32 v[14:15], v[80:81], v[52:53], v[14:15] op_sel:[0,1,0]
	v_pk_fma_f32 v[16:17], v[82:83], v[52:53], v[16:17] op_sel:[0,1,0]
	v_pk_fma_f32 v[10:11], v[80:81], v[56:57], v[10:11] op_sel:[0,1,0]
	v_pk_fma_f32 v[12:13], v[82:83], v[56:57], v[12:13] op_sel:[0,1,0]
	v_pk_fma_f32 v[6:7], v[80:81], v[60:61], v[6:7] op_sel:[0,1,0]
	v_pk_fma_f32 v[8:9], v[82:83], v[60:61], v[8:9] op_sel:[0,1,0]
	v_pk_fma_f32 v[2:3], v[80:81], v[64:65], v[2:3] op_sel:[0,1,0]
	v_pk_fma_f32 v[4:5], v[82:83], v[64:65], v[4:5] op_sel:[0,1,0]
	s_waitcnt vmcnt(13)
	v_pk_fma_f32 v[14:15], v[84:85], v[54:55], v[14:15] op_sel_hi:[1,0,1]
	v_pk_fma_f32 v[16:17], v[86:87], v[54:55], v[16:17] op_sel_hi:[1,0,1]
	v_pk_fma_f32 v[10:11], v[84:85], v[58:59], v[10:11] op_sel_hi:[1,0,1]
	v_pk_fma_f32 v[12:13], v[86:87], v[58:59], v[12:13] op_sel_hi:[1,0,1]
	v_pk_fma_f32 v[6:7], v[84:85], v[62:63], v[6:7] op_sel_hi:[1,0,1]
	v_pk_fma_f32 v[8:9], v[86:87], v[62:63], v[8:9] op_sel_hi:[1,0,1]
	v_pk_fma_f32 v[2:3], v[84:85], v[66:67], v[2:3] op_sel_hi:[1,0,1]
	v_pk_fma_f32 v[4:5], v[86:87], v[66:67], v[4:5] op_sel_hi:[1,0,1]
	s_waitcnt vmcnt(12)
	v_pk_fma_f32 v[14:15], v[88:89], v[68:69], v[14:15] op_sel_hi:[1,0,1]
	v_pk_fma_f32 v[16:17], v[90:91], v[68:69], v[16:17] op_sel_hi:[1,0,1]
	v_pk_fma_f32 v[10:11], v[88:89], v[70:71], v[10:11] op_sel_hi:[1,0,1]
	v_pk_fma_f32 v[12:13], v[90:91], v[70:71], v[12:13] op_sel_hi:[1,0,1]
	v_pk_fma_f32 v[6:7], v[88:89], v[72:73], v[6:7] op_sel_hi:[1,0,1]
	v_pk_fma_f32 v[8:9], v[90:91], v[72:73], v[8:9] op_sel_hi:[1,0,1]
	v_pk_fma_f32 v[2:3], v[88:89], v[74:75], v[2:3] op_sel_hi:[1,0,1]
	v_pk_fma_f32 v[4:5], v[90:91], v[74:75], v[4:5] op_sel_hi:[1,0,1]
	ds_read_b128 v[52:55], v25 offset:208
	ds_read_b128 v[56:59], v25 offset:4304
	ds_read_b128 v[60:63], v25 offset:8400
	ds_read_b128 v[64:67], v25 offset:12496
	s_waitcnt lgkmcnt(0)
	v_mov_b32_e32 v68, v55
	v_mov_b32_e32 v70, v59
	v_mov_b32_e32 v72, v63
	v_mov_b32_e32 v74, v67
	s_waitcnt vmcnt(11)
	v_pk_fma_f32 v[14:15], v[92:93], v[52:53], v[14:15] op_sel_hi:[1,0,1]
	v_pk_fma_f32 v[16:17], v[94:95], v[52:53], v[16:17] op_sel_hi:[1,0,1]
	v_pk_fma_f32 v[10:11], v[92:93], v[56:57], v[10:11] op_sel_hi:[1,0,1]
	v_pk_fma_f32 v[12:13], v[94:95], v[56:57], v[12:13] op_sel_hi:[1,0,1]
	v_pk_fma_f32 v[6:7], v[92:93], v[60:61], v[6:7] op_sel_hi:[1,0,1]
	v_pk_fma_f32 v[8:9], v[94:95], v[60:61], v[8:9] op_sel_hi:[1,0,1]
	v_pk_fma_f32 v[2:3], v[92:93], v[64:65], v[2:3] op_sel_hi:[1,0,1]
	v_pk_fma_f32 v[4:5], v[94:95], v[64:65], v[4:5] op_sel_hi:[1,0,1]
	s_waitcnt vmcnt(10)
	v_pk_fma_f32 v[14:15], v[96:97], v[52:53], v[14:15] op_sel:[0,1,0]
	v_pk_fma_f32 v[16:17], v[98:99], v[52:53], v[16:17] op_sel:[0,1,0]
	v_pk_fma_f32 v[10:11], v[96:97], v[56:57], v[10:11] op_sel:[0,1,0]
	v_pk_fma_f32 v[12:13], v[98:99], v[56:57], v[12:13] op_sel:[0,1,0]
	v_pk_fma_f32 v[6:7], v[96:97], v[60:61], v[6:7] op_sel:[0,1,0]
	v_pk_fma_f32 v[8:9], v[98:99], v[60:61], v[8:9] op_sel:[0,1,0]
	v_pk_fma_f32 v[2:3], v[96:97], v[64:65], v[2:3] op_sel:[0,1,0]
	v_pk_fma_f32 v[4:5], v[98:99], v[64:65], v[4:5] op_sel:[0,1,0]
	s_waitcnt vmcnt(9)
	v_pk_fma_f32 v[14:15], v[100:101], v[54:55], v[14:15] op_sel_hi:[1,0,1]
	v_pk_fma_f32 v[16:17], v[102:103], v[54:55], v[16:17] op_sel_hi:[1,0,1]
	v_pk_fma_f32 v[10:11], v[100:101], v[58:59], v[10:11] op_sel_hi:[1,0,1]
	v_pk_fma_f32 v[12:13], v[102:103], v[58:59], v[12:13] op_sel_hi:[1,0,1]
	v_pk_fma_f32 v[6:7], v[100:101], v[62:63], v[6:7] op_sel_hi:[1,0,1]
	v_pk_fma_f32 v[8:9], v[102:103], v[62:63], v[8:9] op_sel_hi:[1,0,1]
	v_pk_fma_f32 v[2:3], v[100:101], v[66:67], v[2:3] op_sel_hi:[1,0,1]
	v_pk_fma_f32 v[4:5], v[102:103], v[66:67], v[4:5] op_sel_hi:[1,0,1]
	s_waitcnt vmcnt(8)
	v_pk_fma_f32 v[14:15], v[104:105], v[68:69], v[14:15] op_sel_hi:[1,0,1]
	v_pk_fma_f32 v[16:17], v[106:107], v[68:69], v[16:17] op_sel_hi:[1,0,1]
	v_pk_fma_f32 v[10:11], v[104:105], v[70:71], v[10:11] op_sel_hi:[1,0,1]
	v_pk_fma_f32 v[12:13], v[106:107], v[70:71], v[12:13] op_sel_hi:[1,0,1]
	v_pk_fma_f32 v[6:7], v[104:105], v[72:73], v[6:7] op_sel_hi:[1,0,1]
	v_pk_fma_f32 v[8:9], v[106:107], v[72:73], v[8:9] op_sel_hi:[1,0,1]
	v_pk_fma_f32 v[2:3], v[104:105], v[74:75], v[2:3] op_sel_hi:[1,0,1]
	v_pk_fma_f32 v[4:5], v[106:107], v[74:75], v[4:5] op_sel_hi:[1,0,1]
	ds_read_b128 v[52:55], v25 offset:224
	ds_read_b128 v[56:59], v25 offset:4320
	ds_read_b128 v[60:63], v25 offset:8416
	ds_read_b128 v[64:67], v25 offset:12512
	s_waitcnt lgkmcnt(0)
	v_mov_b32_e32 v68, v55
	v_mov_b32_e32 v70, v59
	v_mov_b32_e32 v72, v63
	v_mov_b32_e32 v74, v67
	s_waitcnt vmcnt(7)
	v_pk_fma_f32 v[14:15], v[108:109], v[52:53], v[14:15] op_sel_hi:[1,0,1]
	v_pk_fma_f32 v[16:17], v[110:111], v[52:53], v[16:17] op_sel_hi:[1,0,1]
	v_pk_fma_f32 v[10:11], v[108:109], v[56:57], v[10:11] op_sel_hi:[1,0,1]
	v_pk_fma_f32 v[12:13], v[110:111], v[56:57], v[12:13] op_sel_hi:[1,0,1]
	v_pk_fma_f32 v[6:7], v[108:109], v[60:61], v[6:7] op_sel_hi:[1,0,1]
	v_pk_fma_f32 v[8:9], v[110:111], v[60:61], v[8:9] op_sel_hi:[1,0,1]
	v_pk_fma_f32 v[2:3], v[108:109], v[64:65], v[2:3] op_sel_hi:[1,0,1]
	v_pk_fma_f32 v[4:5], v[110:111], v[64:65], v[4:5] op_sel_hi:[1,0,1]
	s_waitcnt vmcnt(6)
	v_pk_fma_f32 v[14:15], v[112:113], v[52:53], v[14:15] op_sel:[0,1,0]
	v_pk_fma_f32 v[16:17], v[114:115], v[52:53], v[16:17] op_sel:[0,1,0]
	v_pk_fma_f32 v[10:11], v[112:113], v[56:57], v[10:11] op_sel:[0,1,0]
	v_pk_fma_f32 v[12:13], v[114:115], v[56:57], v[12:13] op_sel:[0,1,0]
	v_pk_fma_f32 v[6:7], v[112:113], v[60:61], v[6:7] op_sel:[0,1,0]
	v_pk_fma_f32 v[8:9], v[114:115], v[60:61], v[8:9] op_sel:[0,1,0]
	v_pk_fma_f32 v[2:3], v[112:113], v[64:65], v[2:3] op_sel:[0,1,0]
	v_pk_fma_f32 v[4:5], v[114:115], v[64:65], v[4:5] op_sel:[0,1,0]
	s_waitcnt vmcnt(5)
	v_pk_fma_f32 v[14:15], v[116:117], v[54:55], v[14:15] op_sel_hi:[1,0,1]
	v_pk_fma_f32 v[16:17], v[118:119], v[54:55], v[16:17] op_sel_hi:[1,0,1]
	v_pk_fma_f32 v[10:11], v[116:117], v[58:59], v[10:11] op_sel_hi:[1,0,1]
	v_pk_fma_f32 v[12:13], v[118:119], v[58:59], v[12:13] op_sel_hi:[1,0,1]
	v_pk_fma_f32 v[6:7], v[116:117], v[62:63], v[6:7] op_sel_hi:[1,0,1]
	v_pk_fma_f32 v[8:9], v[118:119], v[62:63], v[8:9] op_sel_hi:[1,0,1]
	v_pk_fma_f32 v[2:3], v[116:117], v[66:67], v[2:3] op_sel_hi:[1,0,1]
	v_pk_fma_f32 v[4:5], v[118:119], v[66:67], v[4:5] op_sel_hi:[1,0,1]
	s_waitcnt vmcnt(4)
	v_pk_fma_f32 v[14:15], v[120:121], v[68:69], v[14:15] op_sel_hi:[1,0,1]
	v_pk_fma_f32 v[16:17], v[122:123], v[68:69], v[16:17] op_sel_hi:[1,0,1]
	v_pk_fma_f32 v[10:11], v[120:121], v[70:71], v[10:11] op_sel_hi:[1,0,1]
	v_pk_fma_f32 v[12:13], v[122:123], v[70:71], v[12:13] op_sel_hi:[1,0,1]
	v_pk_fma_f32 v[6:7], v[120:121], v[72:73], v[6:7] op_sel_hi:[1,0,1]
	v_pk_fma_f32 v[8:9], v[122:123], v[72:73], v[8:9] op_sel_hi:[1,0,1]
	v_pk_fma_f32 v[2:3], v[120:121], v[74:75], v[2:3] op_sel_hi:[1,0,1]
	v_pk_fma_f32 v[4:5], v[122:123], v[74:75], v[4:5] op_sel_hi:[1,0,1]
	ds_read_b128 v[52:55], v25 offset:240
	ds_read_b128 v[56:59], v25 offset:4336
	ds_read_b128 v[60:63], v25 offset:8432
	ds_read_b128 v[64:67], v25 offset:12528
	s_waitcnt lgkmcnt(0)
	v_mov_b32_e32 v68, v55
	v_mov_b32_e32 v70, v59
	v_mov_b32_e32 v72, v63
	v_mov_b32_e32 v74, v67
	s_waitcnt vmcnt(3)
	v_pk_fma_f32 v[14:15], v[124:125], v[52:53], v[14:15] op_sel_hi:[1,0,1]
	v_pk_fma_f32 v[16:17], v[126:127], v[52:53], v[16:17] op_sel_hi:[1,0,1]
	v_pk_fma_f32 v[10:11], v[124:125], v[56:57], v[10:11] op_sel_hi:[1,0,1]
	v_pk_fma_f32 v[12:13], v[126:127], v[56:57], v[12:13] op_sel_hi:[1,0,1]
	v_pk_fma_f32 v[6:7], v[124:125], v[60:61], v[6:7] op_sel_hi:[1,0,1]
	v_pk_fma_f32 v[8:9], v[126:127], v[60:61], v[8:9] op_sel_hi:[1,0,1]
	v_pk_fma_f32 v[2:3], v[124:125], v[64:65], v[2:3] op_sel_hi:[1,0,1]
	v_pk_fma_f32 v[4:5], v[126:127], v[64:65], v[4:5] op_sel_hi:[1,0,1]
	s_waitcnt vmcnt(2)
	v_pk_fma_f32 v[14:15], v[128:129], v[52:53], v[14:15] op_sel:[0,1,0]
	v_pk_fma_f32 v[16:17], v[130:131], v[52:53], v[16:17] op_sel:[0,1,0]
	v_pk_fma_f32 v[10:11], v[128:129], v[56:57], v[10:11] op_sel:[0,1,0]
	v_pk_fma_f32 v[12:13], v[130:131], v[56:57], v[12:13] op_sel:[0,1,0]
	v_pk_fma_f32 v[6:7], v[128:129], v[60:61], v[6:7] op_sel:[0,1,0]
	v_pk_fma_f32 v[8:9], v[130:131], v[60:61], v[8:9] op_sel:[0,1,0]
	v_pk_fma_f32 v[2:3], v[128:129], v[64:65], v[2:3] op_sel:[0,1,0]
	v_pk_fma_f32 v[4:5], v[130:131], v[64:65], v[4:5] op_sel:[0,1,0]
	s_waitcnt vmcnt(1)
	v_pk_fma_f32 v[14:15], v[132:133], v[54:55], v[14:15] op_sel_hi:[1,0,1]
	v_pk_fma_f32 v[16:17], v[134:135], v[54:55], v[16:17] op_sel_hi:[1,0,1]
	v_pk_fma_f32 v[10:11], v[132:133], v[58:59], v[10:11] op_sel_hi:[1,0,1]
	v_pk_fma_f32 v[12:13], v[134:135], v[58:59], v[12:13] op_sel_hi:[1,0,1]
	v_pk_fma_f32 v[6:7], v[132:133], v[62:63], v[6:7] op_sel_hi:[1,0,1]
	v_pk_fma_f32 v[8:9], v[134:135], v[62:63], v[8:9] op_sel_hi:[1,0,1]
	v_pk_fma_f32 v[2:3], v[132:133], v[66:67], v[2:3] op_sel_hi:[1,0,1]
	v_pk_fma_f32 v[4:5], v[134:135], v[66:67], v[4:5] op_sel_hi:[1,0,1]
	s_waitcnt vmcnt(0)
	v_pk_fma_f32 v[14:15], v[136:137], v[68:69], v[14:15] op_sel_hi:[1,0,1]
	v_pk_fma_f32 v[16:17], v[138:139], v[68:69], v[16:17] op_sel_hi:[1,0,1]
	v_pk_fma_f32 v[10:11], v[136:137], v[70:71], v[10:11] op_sel_hi:[1,0,1]
	v_pk_fma_f32 v[12:13], v[138:139], v[70:71], v[12:13] op_sel_hi:[1,0,1]
	v_pk_fma_f32 v[6:7], v[136:137], v[72:73], v[6:7] op_sel_hi:[1,0,1]
	v_pk_fma_f32 v[8:9], v[138:139], v[72:73], v[8:9] op_sel_hi:[1,0,1]
	v_pk_fma_f32 v[2:3], v[136:137], v[74:75], v[2:3] op_sel_hi:[1,0,1]
	v_pk_fma_f32 v[4:5], v[138:139], v[74:75], v[4:5] op_sel_hi:[1,0,1]
	v_lshlrev_b32_e32 v21, 2, v21
	v_mul_hi_i32_i24_e32 v27, 0x14000, v21
	v_mul_i32_i24_e32 v26, 0x14000, v21
	v_ashrrev_i32_e32 v25, 31, v24
	v_lshl_add_u64 v[26:27], s[4:5], 0, v[26:27]
	v_lshlrev_b64 v[24:25], 2, v[24:25]
	v_lshl_add_u64 v[26:27], v[26:27], 0, v[24:25]
	global_store_dwordx4 v[26:27], v[14:17], off
	v_add_u32_e32 v19, s17, v19
	v_cmp_lt_i32_e32 vcc, s22, v19
	v_or_b32_e32 v14, 1, v21
	v_mul_hi_i32_i24_e32 v15, 0x14000, v14
	v_mul_i32_i24_e32 v14, 0x14000, v14
	v_lshl_add_u64 v[14:15], s[4:5], 0, v[14:15]
	v_lshl_add_u64 v[14:15], v[14:15], 0, v[24:25]
	global_store_dwordx4 v[14:15], v[10:13], off
	s_or_b64 s[6:7], vcc, s[6:7]
	s_nop 0
	v_or_b32_e32 v10, 2, v21
	v_mul_hi_i32_i24_e32 v11, 0x14000, v10
	v_mul_i32_i24_e32 v10, 0x14000, v10
	v_lshl_add_u64 v[10:11], s[4:5], 0, v[10:11]
	v_lshl_add_u64 v[10:11], v[10:11], 0, v[24:25]
	global_store_dwordx4 v[10:11], v[6:9], off
	s_nop 1
	v_or_b32_e32 v6, 3, v21
	v_mul_hi_i32_i24_e32 v7, 0x14000, v6
	v_mul_i32_i24_e32 v6, 0x14000, v6
	v_lshl_add_u64 v[6:7], s[4:5], 0, v[6:7]
	v_lshl_add_u64 v[6:7], v[6:7], 0, v[24:25]
	global_store_dwordx4 v[6:7], v[2:5], off
	s_andn2_b64 exec, exec, s[6:7]
	s_cbranch_execnz .LBB0_10

.LBB0_923:
	s_or_b64 exec, exec, s[4:5]
	s_add_i32 s4, s20, s16
	s_lshl_b32 s8, s4, 6
	v_or_b32_e32 v18, s8, v91
	v_cmp_gt_i32_e32 vcc, s19, v18
	v_mov_b32_e32 v2, 0
	v_mov_b32_e32 v3, 0
	v_mov_b32_e32 v4, 0
	v_mov_b32_e32 v5, 0
	v_mov_b32_e32 v6, 0
	v_mov_b32_e32 v7, 0
	v_mov_b32_e32 v8, 0
	v_mov_b32_e32 v9, 0
	v_mov_b32_e32 v10, 0
	v_mov_b32_e32 v11, 0
	v_mov_b32_e32 v12, 0
	v_mov_b32_e32 v13, 0
	v_mov_b32_e32 v14, 0
	v_mov_b32_e32 v15, 0
	v_mov_b32_e32 v16, 0
	v_mov_b32_e32 v17, 0
	s_waitcnt lgkmcnt(0)
	s_barrier
	s_and_saveexec_b64 s[4:5], vcc
	s_cbranch_execz .LBB0_925
	v_ashrrev_i32_e32 v19, 31, v18
	v_lshl_add_u64 v[94:95], v[18:19], 2, s[6:7]
	v_mad_u64_u32 v[2:3], s[6:7], s19, v30, 0
	v_mov_b32_e32 v4, v3
	v_mad_u64_u32 v[4:5], s[6:7], s19, v1, v[4:5]
	v_mov_b32_e32 v3, v4
	v_lshl_add_u64 v[94:95], v[2:3], 2, v[94:95]
	s_lshl_b32 s6, s19, 2
	s_mov_b32 s7, 0
	ds_read_b128 v[142:145], v101
	ds_read_b128 v[106:109], v101 offset:4096
	ds_read_b128 v[236:239], v101 offset:8192
	ds_read_b128 v[18:21], v101 offset:12288
	ds_read_b128 v[146:149], v101 offset:16
	ds_read_b128 v[110:113], v101 offset:4112
	ds_read_b128 v[240:243], v101 offset:8208
	ds_read_b128 v[22:25], v101 offset:12304
	global_load_dwordx4 v[172:175], v[94:95], off
	v_lshl_add_u64 v[94:95], v[94:95], 0, s[6:7]
	global_load_dwordx4 v[176:179], v[94:95], off
	v_lshl_add_u64 v[94:95], v[94:95], 0, s[6:7]
	global_load_dwordx4 v[180:183], v[94:95], off
	v_lshl_add_u64 v[94:95], v[94:95], 0, s[6:7]
	global_load_dwordx4 v[184:187], v[94:95], off
	v_lshl_add_u64 v[94:95], v[94:95], 0, s[6:7]
	global_load_dwordx4 v[188:191], v[94:95], off
	v_lshl_add_u64 v[94:95], v[94:95], 0, s[6:7]
	global_load_dwordx4 v[192:195], v[94:95], off
	v_lshl_add_u64 v[94:95], v[94:95], 0, s[6:7]
	global_load_dwordx4 v[196:199], v[94:95], off
	v_lshl_add_u64 v[94:95], v[94:95], 0, s[6:7]
	global_load_dwordx4 v[200:203], v[94:95], off
	v_lshl_add_u64 v[94:95], v[94:95], 0, s[6:7]
	global_load_dwordx4 v[204:207], v[94:95], off
	v_lshl_add_u64 v[94:95], v[94:95], 0, s[6:7]
	global_load_dwordx4 v[208:211], v[94:95], off
	v_lshl_add_u64 v[94:95], v[94:95], 0, s[6:7]
	global_load_dwordx4 v[212:215], v[94:95], off
	v_lshl_add_u64 v[94:95], v[94:95], 0, s[6:7]
	global_load_dwordx4 v[216:219], v[94:95], off
	v_lshl_add_u64 v[94:95], v[94:95], 0, s[6:7]
	global_load_dwordx4 v[126:129], v[94:95], off
	v_lshl_add_u64 v[94:95], v[94:95], 0, s[6:7]
	global_load_dwordx4 v[130:133], v[94:95], off
	v_lshl_add_u64 v[94:95], v[94:95], 0, s[6:7]
	global_load_dwordx4 v[134:137], v[94:95], off
	v_lshl_add_u64 v[94:95], v[94:95], 0, s[6:7]
	global_load_dwordx4 v[138:141], v[94:95], off
	v_lshl_add_u64 v[94:95], v[94:95], 0, s[6:7]
	s_waitcnt lgkmcnt(0)
	ds_read_b128 v[150:153], v101 offset:32
	ds_read_b128 v[114:117], v101 offset:4128
	ds_read_b128 v[244:247], v101 offset:8224
	ds_read_b128 v[96:99], v101 offset:12320
	ds_read_b128 v[154:157], v101 offset:48
	ds_read_b128 v[118:121], v101 offset:4144
	ds_read_b128 v[248:251], v101 offset:8240
	ds_read_b128 v[158:161], v101 offset:12336
	v_mov_b64_e32 v[2:3], 0
	v_mov_b64_e32 v[4:5], 0
	s_waitcnt vmcnt(15)
	v_pk_fma_f32 v[14:15], v[172:173], v[142:143], v[14:15] op_sel_hi:[1,0,1]
	v_pk_fma_f32 v[16:17], v[174:175], v[142:143], v[16:17] op_sel_hi:[1,0,1]
	v_pk_fma_f32 v[10:11], v[172:173], v[106:107], v[10:11] op_sel_hi:[1,0,1]
	v_pk_fma_f32 v[12:13], v[174:175], v[106:107], v[12:13] op_sel_hi:[1,0,1]
	v_pk_fma_f32 v[6:7], v[172:173], v[236:237], v[6:7] op_sel_hi:[1,0,1]
	v_pk_fma_f32 v[8:9], v[174:175], v[236:237], v[8:9] op_sel_hi:[1,0,1]
	v_pk_fma_f32 v[2:3], v[172:173], v[18:19], v[2:3] op_sel_hi:[1,0,1]
	v_pk_fma_f32 v[4:5], v[174:175], v[18:19], v[4:5] op_sel_hi:[1,0,1]
	global_load_dwordx4 v[172:175], v[94:95], off
	v_lshl_add_u64 v[94:95], v[94:95], 0, s[6:7]
	s_waitcnt vmcnt(15)
	v_pk_fma_f32 v[14:15], v[176:177], v[142:143], v[14:15] op_sel:[0,1,0]
	v_pk_fma_f32 v[16:17], v[178:179], v[142:143], v[16:17] op_sel:[0,1,0]
	v_pk_fma_f32 v[10:11], v[176:177], v[106:107], v[10:11] op_sel:[0,1,0]
	v_pk_fma_f32 v[12:13], v[178:179], v[106:107], v[12:13] op_sel:[0,1,0]
	v_pk_fma_f32 v[6:7], v[176:177], v[236:237], v[6:7] op_sel:[0,1,0]
	v_pk_fma_f32 v[8:9], v[178:179], v[236:237], v[8:9] op_sel:[0,1,0]
	v_pk_fma_f32 v[2:3], v[176:177], v[18:19], v[2:3] op_sel:[0,1,0]
	v_pk_fma_f32 v[4:5], v[178:179], v[18:19], v[4:5] op_sel:[0,1,0]
	global_load_dwordx4 v[176:179], v[94:95], off
	v_lshl_add_u64 v[94:95], v[94:95], 0, s[6:7]
	s_waitcnt vmcnt(15)
	v_pk_fma_f32 v[14:15], v[180:181], v[144:145], v[14:15] op_sel_hi:[1,0,1]
	v_pk_fma_f32 v[16:17], v[182:183], v[144:145], v[16:17] op_sel_hi:[1,0,1]
	v_pk_fma_f32 v[10:11], v[180:181], v[108:109], v[10:11] op_sel_hi:[1,0,1]
	v_pk_fma_f32 v[12:13], v[182:183], v[108:109], v[12:13] op_sel_hi:[1,0,1]
	v_pk_fma_f32 v[6:7], v[180:181], v[238:239], v[6:7] op_sel_hi:[1,0,1]
	v_pk_fma_f32 v[8:9], v[182:183], v[238:239], v[8:9] op_sel_hi:[1,0,1]
	v_pk_fma_f32 v[2:3], v[180:181], v[20:21], v[2:3] op_sel_hi:[1,0,1]
	v_pk_fma_f32 v[4:5], v[182:183], v[20:21], v[4:5] op_sel_hi:[1,0,1]
	global_load_dwordx4 v[180:183], v[94:95], off
	v_lshl_add_u64 v[94:95], v[94:95], 0, s[6:7]
	s_waitcnt vmcnt(15)
	v_pk_fma_f32 v[14:15], v[184:185], v[144:145], v[14:15] op_sel:[0,1,0]
	v_pk_fma_f32 v[16:17], v[186:187], v[144:145], v[16:17] op_sel:[0,1,0]
	v_pk_fma_f32 v[10:11], v[184:185], v[108:109], v[10:11] op_sel:[0,1,0]
	v_pk_fma_f32 v[12:13], v[186:187], v[108:109], v[12:13] op_sel:[0,1,0]
	v_pk_fma_f32 v[6:7], v[184:185], v[238:239], v[6:7] op_sel:[0,1,0]
	v_pk_fma_f32 v[8:9], v[186:187], v[238:239], v[8:9] op_sel:[0,1,0]
	v_pk_fma_f32 v[2:3], v[184:185], v[20:21], v[2:3] op_sel:[0,1,0]
	v_pk_fma_f32 v[4:5], v[186:187], v[20:21], v[4:5] op_sel:[0,1,0]
	global_load_dwordx4 v[184:187], v[94:95], off
	v_lshl_add_u64 v[94:95], v[94:95], 0, s[6:7]
	ds_read_b128 v[142:145], v101 offset:64
	ds_read_b128 v[106:109], v101 offset:4160
	ds_read_b128 v[236:239], v101 offset:8256
	ds_read_b128 v[18:21], v101 offset:12352
	s_waitcnt vmcnt(15)
	v_pk_fma_f32 v[14:15], v[188:189], v[146:147], v[14:15] op_sel_hi:[1,0,1]
	v_pk_fma_f32 v[16:17], v[190:191], v[146:147], v[16:17] op_sel_hi:[1,0,1]
	v_pk_fma_f32 v[10:11], v[188:189], v[110:111], v[10:11] op_sel_hi:[1,0,1]
	v_pk_fma_f32 v[12:13], v[190:191], v[110:111], v[12:13] op_sel_hi:[1,0,1]
	v_pk_fma_f32 v[6:7], v[188:189], v[240:241], v[6:7] op_sel_hi:[1,0,1]
	v_pk_fma_f32 v[8:9], v[190:191], v[240:241], v[8:9] op_sel_hi:[1,0,1]
	v_pk_fma_f32 v[2:3], v[188:189], v[22:23], v[2:3] op_sel_hi:[1,0,1]
	v_pk_fma_f32 v[4:5], v[190:191], v[22:23], v[4:5] op_sel_hi:[1,0,1]
	global_load_dwordx4 v[188:191], v[94:95], off
	v_lshl_add_u64 v[94:95], v[94:95], 0, s[6:7]
	s_waitcnt vmcnt(15)
	v_pk_fma_f32 v[14:15], v[192:193], v[146:147], v[14:15] op_sel:[0,1,0]
	v_pk_fma_f32 v[16:17], v[194:195], v[146:147], v[16:17] op_sel:[0,1,0]
	v_pk_fma_f32 v[10:11], v[192:193], v[110:111], v[10:11] op_sel:[0,1,0]
	v_pk_fma_f32 v[12:13], v[194:195], v[110:111], v[12:13] op_sel:[0,1,0]
	v_pk_fma_f32 v[6:7], v[192:193], v[240:241], v[6:7] op_sel:[0,1,0]
	v_pk_fma_f32 v[8:9], v[194:195], v[240:241], v[8:9] op_sel:[0,1,0]
	v_pk_fma_f32 v[2:3], v[192:193], v[22:23], v[2:3] op_sel:[0,1,0]
	v_pk_fma_f32 v[4:5], v[194:195], v[22:23], v[4:5] op_sel:[0,1,0]
	global_load_dwordx4 v[192:195], v[94:95], off
	v_lshl_add_u64 v[94:95], v[94:95], 0, s[6:7]
	s_waitcnt vmcnt(15)
	v_pk_fma_f32 v[14:15], v[196:197], v[148:149], v[14:15] op_sel_hi:[1,0,1]
	v_pk_fma_f32 v[16:17], v[198:199], v[148:149], v[16:17] op_sel_hi:[1,0,1]
	v_pk_fma_f32 v[10:11], v[196:197], v[112:113], v[10:11] op_sel_hi:[1,0,1]
	v_pk_fma_f32 v[12:13], v[198:199], v[112:113], v[12:13] op_sel_hi:[1,0,1]
	v_pk_fma_f32 v[6:7], v[196:197], v[242:243], v[6:7] op_sel_hi:[1,0,1]
	v_pk_fma_f32 v[8:9], v[198:199], v[242:243], v[8:9] op_sel_hi:[1,0,1]
	v_pk_fma_f32 v[2:3], v[196:197], v[24:25], v[2:3] op_sel_hi:[1,0,1]
	v_pk_fma_f32 v[4:5], v[198:199], v[24:25], v[4:5] op_sel_hi:[1,0,1]
	global_load_dwordx4 v[196:199], v[94:95], off
	v_lshl_add_u64 v[94:95], v[94:95], 0, s[6:7]
	s_waitcnt vmcnt(15)
	v_pk_fma_f32 v[14:15], v[200:201], v[148:149], v[14:15] op_sel:[0,1,0]
	v_pk_fma_f32 v[16:17], v[202:203], v[148:149], v[16:17] op_sel:[0,1,0]
	v_pk_fma_f32 v[10:11], v[200:201], v[112:113], v[10:11] op_sel:[0,1,0]
	v_pk_fma_f32 v[12:13], v[202:203], v[112:113], v[12:13] op_sel:[0,1,0]
	v_pk_fma_f32 v[6:7], v[200:201], v[242:243], v[6:7] op_sel:[0,1,0]
	v_pk_fma_f32 v[8:9], v[202:203], v[242:243], v[8:9] op_sel:[0,1,0]
	v_pk_fma_f32 v[2:3], v[200:201], v[24:25], v[2:3] op_sel:[0,1,0]
	v_pk_fma_f32 v[4:5], v[202:203], v[24:25], v[4:5] op_sel:[0,1,0]
	global_load_dwordx4 v[200:203], v[94:95], off
	v_lshl_add_u64 v[94:95], v[94:95], 0, s[6:7]
	s_waitcnt lgkmcnt(8)
	ds_read_b128 v[146:149], v101 offset:80
	ds_read_b128 v[110:113], v101 offset:4176
	ds_read_b128 v[240:243], v101 offset:8272
	ds_read_b128 v[22:25], v101 offset:12368
	s_waitcnt vmcnt(15)
	v_pk_fma_f32 v[14:15], v[204:205], v[150:151], v[14:15] op_sel_hi:[1,0,1]
	v_pk_fma_f32 v[16:17], v[206:207], v[150:151], v[16:17] op_sel_hi:[1,0,1]
	v_pk_fma_f32 v[10:11], v[204:205], v[114:115], v[10:11] op_sel_hi:[1,0,1]
	v_pk_fma_f32 v[12:13], v[206:207], v[114:115], v[12:13] op_sel_hi:[1,0,1]
	v_pk_fma_f32 v[6:7], v[204:205], v[244:245], v[6:7] op_sel_hi:[1,0,1]
	v_pk_fma_f32 v[8:9], v[206:207], v[244:245], v[8:9] op_sel_hi:[1,0,1]
	v_pk_fma_f32 v[2:3], v[204:205], v[96:97], v[2:3] op_sel_hi:[1,0,1]
	v_pk_fma_f32 v[4:5], v[206:207], v[96:97], v[4:5] op_sel_hi:[1,0,1]
	global_load_dwordx4 v[204:207], v[94:95], off
	v_lshl_add_u64 v[94:95], v[94:95], 0, s[6:7]
	s_waitcnt vmcnt(15)
	v_pk_fma_f32 v[14:15], v[208:209], v[150:151], v[14:15] op_sel:[0,1,0]
	v_pk_fma_f32 v[16:17], v[210:211], v[150:151], v[16:17] op_sel:[0,1,0]
	v_pk_fma_f32 v[10:11], v[208:209], v[114:115], v[10:11] op_sel:[0,1,0]
	v_pk_fma_f32 v[12:13], v[210:211], v[114:115], v[12:13] op_sel:[0,1,0]
	v_pk_fma_f32 v[6:7], v[208:209], v[244:245], v[6:7] op_sel:[0,1,0]
	v_pk_fma_f32 v[8:9], v[210:211], v[244:245], v[8:9] op_sel:[0,1,0]
	v_pk_fma_f32 v[2:3], v[208:209], v[96:97], v[2:3] op_sel:[0,1,0]
	v_pk_fma_f32 v[4:5], v[210:211], v[96:97], v[4:5] op_sel:[0,1,0]
	global_load_dwordx4 v[208:211], v[94:95], off
	v_lshl_add_u64 v[94:95], v[94:95], 0, s[6:7]
	s_waitcnt vmcnt(15)
	v_pk_fma_f32 v[14:15], v[212:213], v[152:153], v[14:15] op_sel_hi:[1,0,1]
	v_pk_fma_f32 v[16:17], v[214:215], v[152:153], v[16:17] op_sel_hi:[1,0,1]
	v_pk_fma_f32 v[10:11], v[212:213], v[116:117], v[10:11] op_sel_hi:[1,0,1]
	v_pk_fma_f32 v[12:13], v[214:215], v[116:117], v[12:13] op_sel_hi:[1,0,1]
	v_pk_fma_f32 v[6:7], v[212:213], v[246:247], v[6:7] op_sel_hi:[1,0,1]
	v_pk_fma_f32 v[8:9], v[214:215], v[246:247], v[8:9] op_sel_hi:[1,0,1]
	v_pk_fma_f32 v[2:3], v[212:213], v[98:99], v[2:3] op_sel_hi:[1,0,1]
	v_pk_fma_f32 v[4:5], v[214:215], v[98:99], v[4:5] op_sel_hi:[1,0,1]
	global_load_dwordx4 v[212:215], v[94:95], off
	v_lshl_add_u64 v[94:95], v[94:95], 0, s[6:7]
	s_waitcnt vmcnt(15)
	v_pk_fma_f32 v[14:15], v[216:217], v[152:153], v[14:15] op_sel:[0,1,0]
	v_pk_fma_f32 v[16:17], v[218:219], v[152:153], v[16:17] op_sel:[0,1,0]
	v_pk_fma_f32 v[10:11], v[216:217], v[116:117], v[10:11] op_sel:[0,1,0]
	v_pk_fma_f32 v[12:13], v[218:219], v[116:117], v[12:13] op_sel:[0,1,0]
	v_pk_fma_f32 v[6:7], v[216:217], v[246:247], v[6:7] op_sel:[0,1,0]
	v_pk_fma_f32 v[8:9], v[218:219], v[246:247], v[8:9] op_sel:[0,1,0]
	v_pk_fma_f32 v[2:3], v[216:217], v[98:99], v[2:3] op_sel:[0,1,0]
	v_pk_fma_f32 v[4:5], v[218:219], v[98:99], v[4:5] op_sel:[0,1,0]
	global_load_dwordx4 v[216:219], v[94:95], off
	v_lshl_add_u64 v[94:95], v[94:95], 0, s[6:7]
	s_waitcnt lgkmcnt(8)
	ds_read_b128 v[150:153], v101 offset:96
	ds_read_b128 v[114:117], v101 offset:4192
	ds_read_b128 v[244:247], v101 offset:8288
	ds_read_b128 v[96:99], v101 offset:12384
	s_waitcnt vmcnt(15)
	v_pk_fma_f32 v[14:15], v[126:127], v[154:155], v[14:15] op_sel_hi:[1,0,1]
	v_pk_fma_f32 v[16:17], v[128:129], v[154:155], v[16:17] op_sel_hi:[1,0,1]
	v_pk_fma_f32 v[10:11], v[126:127], v[118:119], v[10:11] op_sel_hi:[1,0,1]
	v_pk_fma_f32 v[12:13], v[128:129], v[118:119], v[12:13] op_sel_hi:[1,0,1]
	v_pk_fma_f32 v[6:7], v[126:127], v[248:249], v[6:7] op_sel_hi:[1,0,1]
	v_pk_fma_f32 v[8:9], v[128:129], v[248:249], v[8:9] op_sel_hi:[1,0,1]
	v_pk_fma_f32 v[2:3], v[126:127], v[158:159], v[2:3] op_sel_hi:[1,0,1]
	v_pk_fma_f32 v[4:5], v[128:129], v[158:159], v[4:5] op_sel_hi:[1,0,1]
	global_load_dwordx4 v[126:129], v[94:95], off
	v_lshl_add_u64 v[94:95], v[94:95], 0, s[6:7]
	s_waitcnt vmcnt(15)
	v_pk_fma_f32 v[14:15], v[130:131], v[154:155], v[14:15] op_sel:[0,1,0]
	v_pk_fma_f32 v[16:17], v[132:133], v[154:155], v[16:17] op_sel:[0,1,0]
	v_pk_fma_f32 v[10:11], v[130:131], v[118:119], v[10:11] op_sel:[0,1,0]
	v_pk_fma_f32 v[12:13], v[132:133], v[118:119], v[12:13] op_sel:[0,1,0]
	v_pk_fma_f32 v[6:7], v[130:131], v[248:249], v[6:7] op_sel:[0,1,0]
	v_pk_fma_f32 v[8:9], v[132:133], v[248:249], v[8:9] op_sel:[0,1,0]
	v_pk_fma_f32 v[2:3], v[130:131], v[158:159], v[2:3] op_sel:[0,1,0]
	v_pk_fma_f32 v[4:5], v[132:133], v[158:159], v[4:5] op_sel:[0,1,0]
	global_load_dwordx4 v[130:133], v[94:95], off
	v_lshl_add_u64 v[94:95], v[94:95], 0, s[6:7]
	s_waitcnt vmcnt(15)
	v_pk_fma_f32 v[14:15], v[134:135], v[156:157], v[14:15] op_sel_hi:[1,0,1]
	v_pk_fma_f32 v[16:17], v[136:137], v[156:157], v[16:17] op_sel_hi:[1,0,1]
	v_pk_fma_f32 v[10:11], v[134:135], v[120:121], v[10:11] op_sel_hi:[1,0,1]
	v_pk_fma_f32 v[12:13], v[136:137], v[120:121], v[12:13] op_sel_hi:[1,0,1]
	v_pk_fma_f32 v[6:7], v[134:135], v[250:251], v[6:7] op_sel_hi:[1,0,1]
	v_pk_fma_f32 v[8:9], v[136:137], v[250:251], v[8:9] op_sel_hi:[1,0,1]
	v_pk_fma_f32 v[2:3], v[134:135], v[160:161], v[2:3] op_sel_hi:[1,0,1]
	v_pk_fma_f32 v[4:5], v[136:137], v[160:161], v[4:5] op_sel_hi:[1,0,1]
	global_load_dwordx4 v[134:137], v[94:95], off
	v_lshl_add_u64 v[94:95], v[94:95], 0, s[6:7]
	s_waitcnt vmcnt(15)
	v_pk_fma_f32 v[14:15], v[138:139], v[156:157], v[14:15] op_sel:[0,1,0]
	v_pk_fma_f32 v[16:17], v[140:141], v[156:157], v[16:17] op_sel:[0,1,0]
	v_pk_fma_f32 v[10:11], v[138:139], v[120:121], v[10:11] op_sel:[0,1,0]
	v_pk_fma_f32 v[12:13], v[140:141], v[120:121], v[12:13] op_sel:[0,1,0]
	v_pk_fma_f32 v[6:7], v[138:139], v[250:251], v[6:7] op_sel:[0,1,0]
	v_pk_fma_f32 v[8:9], v[140:141], v[250:251], v[8:9] op_sel:[0,1,0]
	v_pk_fma_f32 v[2:3], v[138:139], v[160:161], v[2:3] op_sel:[0,1,0]
	v_pk_fma_f32 v[4:5], v[140:141], v[160:161], v[4:5] op_sel:[0,1,0]
	global_load_dwordx4 v[138:141], v[94:95], off
	v_lshl_add_u64 v[94:95], v[94:95], 0, s[6:7]
	s_waitcnt lgkmcnt(8)
	ds_read_b128 v[154:157], v101 offset:112
	ds_read_b128 v[118:121], v101 offset:4208
	ds_read_b128 v[248:251], v101 offset:8304
	ds_read_b128 v[158:161], v101 offset:12400
	s_waitcnt vmcnt(15)
	v_pk_fma_f32 v[14:15], v[172:173], v[142:143], v[14:15] op_sel_hi:[1,0,1]
	v_pk_fma_f32 v[16:17], v[174:175], v[142:143], v[16:17] op_sel_hi:[1,0,1]
	v_pk_fma_f32 v[10:11], v[172:173], v[106:107], v[10:11] op_sel_hi:[1,0,1]
	v_pk_fma_f32 v[12:13], v[174:175], v[106:107], v[12:13] op_sel_hi:[1,0,1]
	v_pk_fma_f32 v[6:7], v[172:173], v[236:237], v[6:7] op_sel_hi:[1,0,1]
	v_pk_fma_f32 v[8:9], v[174:175], v[236:237], v[8:9] op_sel_hi:[1,0,1]
	v_pk_fma_f32 v[2:3], v[172:173], v[18:19], v[2:3] op_sel_hi:[1,0,1]
	v_pk_fma_f32 v[4:5], v[174:175], v[18:19], v[4:5] op_sel_hi:[1,0,1]
	s_waitcnt vmcnt(14)
	v_pk_fma_f32 v[14:15], v[176:177], v[142:143], v[14:15] op_sel:[0,1,0]
	v_pk_fma_f32 v[16:17], v[178:179], v[142:143], v[16:17] op_sel:[0,1,0]
	v_pk_fma_f32 v[10:11], v[176:177], v[106:107], v[10:11] op_sel:[0,1,0]
	v_pk_fma_f32 v[12:13], v[178:179], v[106:107], v[12:13] op_sel:[0,1,0]
	v_pk_fma_f32 v[6:7], v[176:177], v[236:237], v[6:7] op_sel:[0,1,0]
	v_pk_fma_f32 v[8:9], v[178:179], v[236:237], v[8:9] op_sel:[0,1,0]
	v_pk_fma_f32 v[2:3], v[176:177], v[18:19], v[2:3] op_sel:[0,1,0]
	v_pk_fma_f32 v[4:5], v[178:179], v[18:19], v[4:5] op_sel:[0,1,0]
	s_waitcnt vmcnt(13)
	v_pk_fma_f32 v[14:15], v[180:181], v[144:145], v[14:15] op_sel_hi:[1,0,1]
	v_pk_fma_f32 v[16:17], v[182:183], v[144:145], v[16:17] op_sel_hi:[1,0,1]
	v_pk_fma_f32 v[10:11], v[180:181], v[108:109], v[10:11] op_sel_hi:[1,0,1]
	v_pk_fma_f32 v[12:13], v[182:183], v[108:109], v[12:13] op_sel_hi:[1,0,1]
	v_pk_fma_f32 v[6:7], v[180:181], v[238:239], v[6:7] op_sel_hi:[1,0,1]
	v_pk_fma_f32 v[8:9], v[182:183], v[238:239], v[8:9] op_sel_hi:[1,0,1]
	v_pk_fma_f32 v[2:3], v[180:181], v[20:21], v[2:3] op_sel_hi:[1,0,1]
	v_pk_fma_f32 v[4:5], v[182:183], v[20:21], v[4:5] op_sel_hi:[1,0,1]
	s_waitcnt vmcnt(12)
	v_pk_fma_f32 v[14:15], v[184:185], v[144:145], v[14:15] op_sel:[0,1,0]
	v_pk_fma_f32 v[16:17], v[186:187], v[144:145], v[16:17] op_sel:[0,1,0]
	v_pk_fma_f32 v[10:11], v[184:185], v[108:109], v[10:11] op_sel:[0,1,0]
	v_pk_fma_f32 v[12:13], v[186:187], v[108:109], v[12:13] op_sel:[0,1,0]
	v_pk_fma_f32 v[6:7], v[184:185], v[238:239], v[6:7] op_sel:[0,1,0]
	v_pk_fma_f32 v[8:9], v[186:187], v[238:239], v[8:9] op_sel:[0,1,0]
	v_pk_fma_f32 v[2:3], v[184:185], v[20:21], v[2:3] op_sel:[0,1,0]
	v_pk_fma_f32 v[4:5], v[186:187], v[20:21], v[4:5] op_sel:[0,1,0]
	s_waitcnt lgkmcnt(8)
	s_waitcnt vmcnt(11)
	v_pk_fma_f32 v[14:15], v[188:189], v[146:147], v[14:15] op_sel_hi:[1,0,1]
	v_pk_fma_f32 v[16:17], v[190:191], v[146:147], v[16:17] op_sel_hi:[1,0,1]
	v_pk_fma_f32 v[10:11], v[188:189], v[110:111], v[10:11] op_sel_hi:[1,0,1]
	v_pk_fma_f32 v[12:13], v[190:191], v[110:111], v[12:13] op_sel_hi:[1,0,1]
	v_pk_fma_f32 v[6:7], v[188:189], v[240:241], v[6:7] op_sel_hi:[1,0,1]
	v_pk_fma_f32 v[8:9], v[190:191], v[240:241], v[8:9] op_sel_hi:[1,0,1]
	v_pk_fma_f32 v[2:3], v[188:189], v[22:23], v[2:3] op_sel_hi:[1,0,1]
	v_pk_fma_f32 v[4:5], v[190:191], v[22:23], v[4:5] op_sel_hi:[1,0,1]
	s_waitcnt vmcnt(10)
	v_pk_fma_f32 v[14:15], v[192:193], v[146:147], v[14:15] op_sel:[0,1,0]
	v_pk_fma_f32 v[16:17], v[194:195], v[146:147], v[16:17] op_sel:[0,1,0]
	v_pk_fma_f32 v[10:11], v[192:193], v[110:111], v[10:11] op_sel:[0,1,0]
	v_pk_fma_f32 v[12:13], v[194:195], v[110:111], v[12:13] op_sel:[0,1,0]
	v_pk_fma_f32 v[6:7], v[192:193], v[240:241], v[6:7] op_sel:[0,1,0]
	v_pk_fma_f32 v[8:9], v[194:195], v[240:241], v[8:9] op_sel:[0,1,0]
	v_pk_fma_f32 v[2:3], v[192:193], v[22:23], v[2:3] op_sel:[0,1,0]
	v_pk_fma_f32 v[4:5], v[194:195], v[22:23], v[4:5] op_sel:[0,1,0]
	s_waitcnt vmcnt(9)
	v_pk_fma_f32 v[14:15], v[196:197], v[148:149], v[14:15] op_sel_hi:[1,0,1]
	v_pk_fma_f32 v[16:17], v[198:199], v[148:149], v[16:17] op_sel_hi:[1,0,1]
	v_pk_fma_f32 v[10:11], v[196:197], v[112:113], v[10:11] op_sel_hi:[1,0,1]
	v_pk_fma_f32 v[12:13], v[198:199], v[112:113], v[12:13] op_sel_hi:[1,0,1]
	v_pk_fma_f32 v[6:7], v[196:197], v[242:243], v[6:7] op_sel_hi:[1,0,1]
	v_pk_fma_f32 v[8:9], v[198:199], v[242:243], v[8:9] op_sel_hi:[1,0,1]
	v_pk_fma_f32 v[2:3], v[196:197], v[24:25], v[2:3] op_sel_hi:[1,0,1]
	v_pk_fma_f32 v[4:5], v[198:199], v[24:25], v[4:5] op_sel_hi:[1,0,1]
	s_waitcnt vmcnt(8)
	v_pk_fma_f32 v[14:15], v[200:201], v[148:149], v[14:15] op_sel:[0,1,0]
	v_pk_fma_f32 v[16:17], v[202:203], v[148:149], v[16:17] op_sel:[0,1,0]
	v_pk_fma_f32 v[10:11], v[200:201], v[112:113], v[10:11] op_sel:[0,1,0]
	v_pk_fma_f32 v[12:13], v[202:203], v[112:113], v[12:13] op_sel:[0,1,0]
	v_pk_fma_f32 v[6:7], v[200:201], v[242:243], v[6:7] op_sel:[0,1,0]
	v_pk_fma_f32 v[8:9], v[202:203], v[242:243], v[8:9] op_sel:[0,1,0]
	v_pk_fma_f32 v[2:3], v[200:201], v[24:25], v[2:3] op_sel:[0,1,0]
	v_pk_fma_f32 v[4:5], v[202:203], v[24:25], v[4:5] op_sel:[0,1,0]
	s_waitcnt lgkmcnt(4)
	s_waitcnt vmcnt(7)
	v_pk_fma_f32 v[14:15], v[204:205], v[150:151], v[14:15] op_sel_hi:[1,0,1]
	v_pk_fma_f32 v[16:17], v[206:207], v[150:151], v[16:17] op_sel_hi:[1,0,1]
	v_pk_fma_f32 v[10:11], v[204:205], v[114:115], v[10:11] op_sel_hi:[1,0,1]
	v_pk_fma_f32 v[12:13], v[206:207], v[114:115], v[12:13] op_sel_hi:[1,0,1]
	v_pk_fma_f32 v[6:7], v[204:205], v[244:245], v[6:7] op_sel_hi:[1,0,1]
	v_pk_fma_f32 v[8:9], v[206:207], v[244:245], v[8:9] op_sel_hi:[1,0,1]
	v_pk_fma_f32 v[2:3], v[204:205], v[96:97], v[2:3] op_sel_hi:[1,0,1]
	v_pk_fma_f32 v[4:5], v[206:207], v[96:97], v[4:5] op_sel_hi:[1,0,1]
	s_waitcnt vmcnt(6)
	v_pk_fma_f32 v[14:15], v[208:209], v[150:151], v[14:15] op_sel:[0,1,0]
	v_pk_fma_f32 v[16:17], v[210:211], v[150:151], v[16:17] op_sel:[0,1,0]
	v_pk_fma_f32 v[10:11], v[208:209], v[114:115], v[10:11] op_sel:[0,1,0]
	v_pk_fma_f32 v[12:13], v[210:211], v[114:115], v[12:13] op_sel:[0,1,0]
	v_pk_fma_f32 v[6:7], v[208:209], v[244:245], v[6:7] op_sel:[0,1,0]
	v_pk_fma_f32 v[8:9], v[210:211], v[244:245], v[8:9] op_sel:[0,1,0]
	v_pk_fma_f32 v[2:3], v[208:209], v[96:97], v[2:3] op_sel:[0,1,0]
	v_pk_fma_f32 v[4:5], v[210:211], v[96:97], v[4:5] op_sel:[0,1,0]
	s_waitcnt vmcnt(5)
	v_pk_fma_f32 v[14:15], v[212:213], v[152:153], v[14:15] op_sel_hi:[1,0,1]
	v_pk_fma_f32 v[16:17], v[214:215], v[152:153], v[16:17] op_sel_hi:[1,0,1]
	v_pk_fma_f32 v[10:11], v[212:213], v[116:117], v[10:11] op_sel_hi:[1,0,1]
	v_pk_fma_f32 v[12:13], v[214:215], v[116:117], v[12:13] op_sel_hi:[1,0,1]
	v_pk_fma_f32 v[6:7], v[212:213], v[246:247], v[6:7] op_sel_hi:[1,0,1]
	v_pk_fma_f32 v[8:9], v[214:215], v[246:247], v[8:9] op_sel_hi:[1,0,1]
	v_pk_fma_f32 v[2:3], v[212:213], v[98:99], v[2:3] op_sel_hi:[1,0,1]
	v_pk_fma_f32 v[4:5], v[214:215], v[98:99], v[4:5] op_sel_hi:[1,0,1]
	s_waitcnt vmcnt(4)
	v_pk_fma_f32 v[14:15], v[216:217], v[152:153], v[14:15] op_sel:[0,1,0]
	v_pk_fma_f32 v[16:17], v[218:219], v[152:153], v[16:17] op_sel:[0,1,0]
	v_pk_fma_f32 v[10:11], v[216:217], v[116:117], v[10:11] op_sel:[0,1,0]
	v_pk_fma_f32 v[12:13], v[218:219], v[116:117], v[12:13] op_sel:[0,1,0]
	v_pk_fma_f32 v[6:7], v[216:217], v[246:247], v[6:7] op_sel:[0,1,0]
	v_pk_fma_f32 v[8:9], v[218:219], v[246:247], v[8:9] op_sel:[0,1,0]
	v_pk_fma_f32 v[2:3], v[216:217], v[98:99], v[2:3] op_sel:[0,1,0]
	v_pk_fma_f32 v[4:5], v[218:219], v[98:99], v[4:5] op_sel:[0,1,0]
	s_waitcnt lgkmcnt(0)
	s_waitcnt vmcnt(3)
	v_pk_fma_f32 v[14:15], v[126:127], v[154:155], v[14:15] op_sel_hi:[1,0,1]
	v_pk_fma_f32 v[16:17], v[128:129], v[154:155], v[16:17] op_sel_hi:[1,0,1]
	v_pk_fma_f32 v[10:11], v[126:127], v[118:119], v[10:11] op_sel_hi:[1,0,1]
	v_pk_fma_f32 v[12:13], v[128:129], v[118:119], v[12:13] op_sel_hi:[1,0,1]
	v_pk_fma_f32 v[6:7], v[126:127], v[248:249], v[6:7] op_sel_hi:[1,0,1]
	v_pk_fma_f32 v[8:9], v[128:129], v[248:249], v[8:9] op_sel_hi:[1,0,1]
	v_pk_fma_f32 v[2:3], v[126:127], v[158:159], v[2:3] op_sel_hi:[1,0,1]
	v_pk_fma_f32 v[4:5], v[128:129], v[158:159], v[4:5] op_sel_hi:[1,0,1]
	s_waitcnt vmcnt(2)
	v_pk_fma_f32 v[14:15], v[130:131], v[154:155], v[14:15] op_sel:[0,1,0]
	v_pk_fma_f32 v[16:17], v[132:133], v[154:155], v[16:17] op_sel:[0,1,0]
	v_pk_fma_f32 v[10:11], v[130:131], v[118:119], v[10:11] op_sel:[0,1,0]
	v_pk_fma_f32 v[12:13], v[132:133], v[118:119], v[12:13] op_sel:[0,1,0]
	v_pk_fma_f32 v[6:7], v[130:131], v[248:249], v[6:7] op_sel:[0,1,0]
	v_pk_fma_f32 v[8:9], v[132:133], v[248:249], v[8:9] op_sel:[0,1,0]
	v_pk_fma_f32 v[2:3], v[130:131], v[158:159], v[2:3] op_sel:[0,1,0]
	v_pk_fma_f32 v[4:5], v[132:133], v[158:159], v[4:5] op_sel:[0,1,0]
	s_waitcnt vmcnt(1)
	v_pk_fma_f32 v[14:15], v[134:135], v[156:157], v[14:15] op_sel_hi:[1,0,1]
	v_pk_fma_f32 v[16:17], v[136:137], v[156:157], v[16:17] op_sel_hi:[1,0,1]
	v_pk_fma_f32 v[10:11], v[134:135], v[120:121], v[10:11] op_sel_hi:[1,0,1]
	v_pk_fma_f32 v[12:13], v[136:137], v[120:121], v[12:13] op_sel_hi:[1,0,1]
	v_pk_fma_f32 v[6:7], v[134:135], v[250:251], v[6:7] op_sel_hi:[1,0,1]
	v_pk_fma_f32 v[8:9], v[136:137], v[250:251], v[8:9] op_sel_hi:[1,0,1]
	v_pk_fma_f32 v[2:3], v[134:135], v[160:161], v[2:3] op_sel_hi:[1,0,1]
	v_pk_fma_f32 v[4:5], v[136:137], v[160:161], v[4:5] op_sel_hi:[1,0,1]
	s_waitcnt vmcnt(0)
	v_pk_fma_f32 v[14:15], v[138:139], v[156:157], v[14:15] op_sel:[0,1,0]
	v_pk_fma_f32 v[16:17], v[140:141], v[156:157], v[16:17] op_sel:[0,1,0]
	v_pk_fma_f32 v[10:11], v[138:139], v[120:121], v[10:11] op_sel:[0,1,0]
	v_pk_fma_f32 v[12:13], v[140:141], v[120:121], v[12:13] op_sel:[0,1,0]
	v_pk_fma_f32 v[6:7], v[138:139], v[250:251], v[6:7] op_sel:[0,1,0]
	v_pk_fma_f32 v[8:9], v[140:141], v[250:251], v[8:9] op_sel:[0,1,0]
	v_pk_fma_f32 v[2:3], v[138:139], v[160:161], v[2:3] op_sel:[0,1,0]
	v_pk_fma_f32 v[4:5], v[140:141], v[160:161], v[4:5] op_sel:[0,1,0]
